# v61 + s_setprio 2 from each K-loop barrier to the end of the fragment reads in the GLU and out-proj GEMM loops
# speedup vs baseline: 1.0109x; 1.0062x over previous
.LBB0_743:
	s_ashr_i32 s8, s6, 31
	s_lshr_b32 s8, s8, 27
	s_add_i32 s8, s6, s8
	s_ashr_i32 s8, s8, 5
	s_lshl_b32 s9, s8, 10
	s_and_b32 s16, s10, 0x380
	s_or_b32 s16, s9, s16
	v_add_u32_e32 v0, s16, v137
	v_ashrrev_i32_e32 v1, 31, v0
	v_lshlrev_b64 v[0:1], 10, v[0:1]
	s_lshl_b32 s8, s8, 9
	v_lshl_add_u64 v[158:159], v[208:209], 0, v[0:1]
	s_sub_i32 s8, s12, s8
	v_add_co_u32_e32 v160, vcc, s27, v158
	s_and_b32 s8, s8, 0xffffff80
	s_nop 0
	v_addc_co_u32_e32 v161, vcc, 0, v159, vcc
	v_add_u32_e32 v0, s8, v137
	v_add_co_u32_e32 v156, vcc, s22, v158
	v_ashrrev_i32_e32 v1, 31, v0
	s_nop 0
	v_addc_co_u32_e32 v157, vcc, 0, v159, vcc
	v_lshlrev_b64 v[0:1], 10, v[0:1]
	v_add_co_u32_e32 v154, vcc, s28, v158
	v_lshl_add_u64 v[140:141], v[250:251], 0, v[0:1]
	s_nop 0
	v_addc_co_u32_e32 v155, vcc, 0, v159, vcc
	v_add_co_u32_e32 v150, vcc, s27, v140
	global_load_dwordx4 v[0:3], v[158:159], off
	s_nop 0
	v_addc_co_u32_e32 v151, vcc, 0, v141, vcc
	v_add_co_u32_e32 v152, vcc, s22, v140
	global_load_dwordx4 v[4:7], v[160:161], off
	s_nop 0
	v_addc_co_u32_e32 v153, vcc, 0, v141, vcc
	v_add_co_u32_e32 v142, vcc, s28, v140
	global_load_dwordx4 v[8:11], v[156:157], off
	s_nop 0
	v_addc_co_u32_e32 v143, vcc, 0, v141, vcc
	global_load_dwordx4 v[12:15], v[154:155], off
	global_load_dwordx4 v[16:19], v[140:141], off
	global_load_dwordx4 v[20:23], v[150:151], off
	global_load_dwordx4 v[24:27], v[152:153], off
	global_load_dwordx4 v[28:31], v[142:143], off
	global_load_dwordx4 v[32:35], v[158:159], off offset:128
	global_load_dwordx4 v[36:39], v[160:161], off offset:128
	global_load_dwordx4 v[48:51], v[154:155], off offset:128
	global_load_dwordx4 v[52:55], v[152:153], off offset:128
	global_load_dwordx4 v[64:67], v[158:159], off offset:256
	global_load_dwordx4 v[68:71], v[160:161], off offset:256
	global_load_dwordx4 v[56:59], v[156:157], off offset:128
	global_load_dwordx4 v[72:75], v[156:157], off offset:256
	global_load_dwordx4 v[76:79], v[154:155], off offset:256
	global_load_dwordx4 v[60:63], v[140:141], off offset:128
	global_load_dwordx4 v[80:83], v[140:141], off offset:256
	global_load_dwordx4 v[112:115], v[150:151], off offset:128
	global_load_dwordx4 v[84:87], v[150:151], off offset:256
	global_load_dwordx4 v[88:91], v[152:153], off offset:256
	global_load_dwordx4 v[124:127], v[142:143], off offset:128
	global_load_dwordx4 v[120:123], v[142:143], off offset:256
	s_waitcnt vmcnt(23)
	ds_write_b128 v132, v[0:3]
	s_waitcnt vmcnt(22)
	ds_write_b128 v132, v[4:7] offset:4608
	s_waitcnt vmcnt(21)
	ds_write_b128 v132, v[8:11] offset:9216
	s_waitcnt vmcnt(20)
	ds_write_b128 v132, v[12:15] offset:13824
	s_waitcnt vmcnt(19)
	ds_write_b128 v132, v[16:19] offset:36864
	s_waitcnt vmcnt(18)
	ds_write_b128 v132, v[20:23] offset:41472
	s_waitcnt vmcnt(17)
	ds_write_b128 v132, v[24:27] offset:46080
	s_waitcnt vmcnt(16)
	ds_write_b128 v132, v[28:31] offset:50688
	s_waitcnt lgkmcnt(0)
	s_barrier
	s_setprio 2
	ds_read_b128 v[168:171], v134
	ds_read_b128 v[172:175], v134 offset:32
	ds_read_b128 v[176:179], v133 offset:36864
	ds_read_b128 v[180:183], v133 offset:36896
	ds_read_b128 v[16:19], v134 offset:4608
	ds_read_b128 v[104:107], v134 offset:4640
	ds_read_b128 v[20:23], v133 offset:41472
	ds_read_b128 v[108:111], v133 offset:41504
	ds_read_b128 v[184:187], v134 offset:64
	ds_read_b128 v[188:191], v134 offset:96
	ds_read_b128 v[210:213], v133 offset:36928
	ds_read_b128 v[214:217], v133 offset:36960
	ds_read_b128 v[116:119], v134 offset:4672
	ds_read_b128 v[218:221], v134 offset:4704
	ds_read_b128 v[222:225], v133 offset:41536
	ds_read_b128 v[226:229], v133 offset:41568
	s_setprio 0
	s_waitcnt lgkmcnt(11)
	v_mfma_f32_32x32x16_bf16 v[0:15], v[16:19], v[176:179], 0
	s_waitcnt lgkmcnt(10)
	v_mfma_f32_32x32x16_bf16 v[0:15], v[104:107], v[180:183], v[0:15]
	s_waitcnt vmcnt(15)
	ds_write_b128 v132, v[32:35] offset:18432
	global_load_dwordx4 v[92:95], v[158:159], off offset:384
	s_waitcnt lgkmcnt(4)
	v_mfma_f32_32x32x16_bf16 v[0:15], v[116:119], v[210:213], v[0:15]
	s_waitcnt lgkmcnt(3)
	v_mfma_f32_32x32x16_bf16 v[0:15], v[218:221], v[214:217], v[0:15]
	s_waitcnt vmcnt(15)
	ds_write_b128 v132, v[36:39] offset:23040
	global_load_dwordx4 v[96:99], v[160:161], off offset:384
	v_mfma_f32_32x32x16_bf16 v[32:47], v[168:171], v[20:23], 0
	v_mfma_f32_32x32x16_bf16 v[16:31], v[16:19], v[20:23], 0
	s_waitcnt vmcnt(11)
	ds_write_b128 v132, v[56:59] offset:27648
	global_load_dwordx4 v[100:103], v[156:157], off offset:384
	v_mfma_f32_32x32x16_bf16 v[32:47], v[172:175], v[108:111], v[32:47]
	v_mfma_f32_32x32x16_bf16 v[16:31], v[104:107], v[108:111], v[16:31]
	ds_write_b128 v132, v[48:51] offset:32256
	global_load_dwordx4 v[104:107], v[154:155], off offset:384
	s_waitcnt lgkmcnt(5)
	v_mfma_f32_32x32x16_bf16 v[32:47], v[184:187], v[222:225], v[32:47]
	v_mfma_f32_32x32x16_bf16 v[16:31], v[116:119], v[222:225], v[16:31]
	s_waitcnt vmcnt(10)
	ds_write_b128 v132, v[60:63] offset:55296
	global_load_dwordx4 v[108:111], v[140:141], off offset:384
	s_waitcnt vmcnt(9)
	ds_write_b128 v132, v[112:115] offset:59904
	global_load_dwordx4 v[112:115], v[150:151], off offset:384
	ds_write_b128 v132, v[52:55] offset:64512
	global_load_dwordx4 v[116:119], v[152:153], off offset:384
	s_waitcnt vmcnt(8)
	ds_write_b128 v135, v[124:127] offset:13824
	global_load_dwordx4 v[124:127], v[142:143], off offset:384
	s_waitcnt lgkmcnt(0)
	s_barrier
	s_setprio 2
	v_mfma_f32_32x32x16_bf16 v[32:47], v[188:191], v[226:229], v[32:47]
	v_mfma_f32_32x32x16_bf16 v[48:63], v[168:171], v[176:179], 0
	ds_read_b128 v[168:171], v134 offset:18432
	ds_read_b128 v[176:179], v133 offset:55296
	ds_read_b128 v[222:225], v133 offset:59904
	ds_read_b128 v[230:233], v133 offset:59936
	ds_read_b128 v[234:237], v133 offset:55360
	ds_read_b128 v[238:241], v133 offset:55392
	ds_read_b128 v[242:245], v134 offset:23104
	v_mfma_f32_32x32x16_bf16 v[48:63], v[172:175], v[180:183], v[48:63]
	ds_read_b128 v[172:175], v134 offset:18464
	ds_read_b128 v[180:183], v133 offset:55328
	ds_read_b128 v[246:249], v134 offset:23136
	ds_read_b128 v[128:131], v133 offset:59968
	ds_read_b128 v[146:149], v133 offset:60000
	v_mfma_f32_32x32x16_bf16 v[48:63], v[184:187], v[210:213], v[48:63]
	ds_read_b128 v[184:187], v134 offset:23040
	ds_read_b128 v[210:213], v134 offset:23072
	v_mfma_f32_32x32x16_bf16 v[48:63], v[188:191], v[214:217], v[48:63]
	ds_read_b128 v[188:191], v134 offset:18496
	ds_read_b128 v[214:217], v134 offset:18528
	s_setprio 0
	v_mfma_f32_32x32x16_bf16 v[16:31], v[218:221], v[226:229], v[16:31]
	s_waitcnt lgkmcnt(3)
	v_mfma_f32_32x32x16_bf16 v[0:15], v[184:187], v[176:179], v[0:15]
	s_waitcnt lgkmcnt(2)
	v_mfma_f32_32x32x16_bf16 v[0:15], v[210:213], v[180:183], v[0:15]
	ds_write_b128 v132, v[64:67]
	global_load_dwordx4 v[64:67], v[158:159], off offset:512
	v_mfma_f32_32x32x16_bf16 v[0:15], v[242:245], v[234:237], v[0:15]
	v_mfma_f32_32x32x16_bf16 v[0:15], v[246:249], v[238:241], v[0:15]
	ds_write_b128 v132, v[68:71] offset:4608
	global_load_dwordx4 v[68:71], v[160:161], off offset:512
	v_mfma_f32_32x32x16_bf16 v[48:63], v[168:171], v[176:179], v[48:63]
	v_mfma_f32_32x32x16_bf16 v[32:47], v[168:171], v[222:225], v[32:47]
	ds_write_b128 v132, v[72:75] offset:9216
	global_load_dwordx4 v[72:75], v[156:157], off offset:512
	v_mfma_f32_32x32x16_bf16 v[16:31], v[184:187], v[222:225], v[16:31]
	v_mfma_f32_32x32x16_bf16 v[48:63], v[172:175], v[180:183], v[48:63]
	ds_write_b128 v132, v[76:79] offset:13824
	global_load_dwordx4 v[76:79], v[154:155], off offset:512
	v_mfma_f32_32x32x16_bf16 v[32:47], v[172:175], v[230:233], v[32:47]
	v_mfma_f32_32x32x16_bf16 v[16:31], v[210:213], v[230:233], v[16:31]
	ds_write_b128 v132, v[80:83] offset:36864
	global_load_dwordx4 v[80:83], v[140:141], off offset:512
	s_waitcnt lgkmcnt(6)
	v_mfma_f32_32x32x16_bf16 v[48:63], v[188:191], v[234:237], v[48:63]
	v_mfma_f32_32x32x16_bf16 v[32:47], v[188:191], v[128:131], v[32:47]
	ds_write_b128 v132, v[84:87] offset:41472
	global_load_dwordx4 v[84:87], v[150:151], off offset:512
	v_mfma_f32_32x32x16_bf16 v[16:31], v[242:245], v[128:131], v[16:31]
	s_waitcnt lgkmcnt(6)
	v_mfma_f32_32x32x16_bf16 v[48:63], v[214:217], v[238:241], v[48:63]
	ds_write_b128 v132, v[88:91] offset:46080
	global_load_dwordx4 v[88:91], v[152:153], off offset:512
	v_mfma_f32_32x32x16_bf16 v[32:47], v[214:217], v[146:149], v[32:47]
	s_waitcnt vmcnt(15)
	ds_write_b128 v132, v[120:123] offset:50688
	global_load_dwordx4 v[120:123], v[142:143], off offset:512
	s_waitcnt lgkmcnt(0)
	s_barrier
	s_setprio 2
	v_mfma_f32_32x32x16_bf16 v[16:31], v[246:249], v[146:149], v[16:31]
	ds_read_b128 v[128:131], v134
	ds_read_b128 v[146:149], v134 offset:32
	ds_read_b128 v[168:171], v133 offset:36864
	ds_read_b128 v[172:175], v133 offset:36896
	ds_read_b128 v[176:179], v134 offset:4608
	ds_read_b128 v[180:183], v134 offset:4640
	ds_read_b128 v[184:187], v133 offset:41472
	ds_read_b128 v[188:191], v133 offset:41504
	ds_read_b128 v[210:213], v134 offset:64
	ds_read_b128 v[214:217], v134 offset:96
	ds_read_b128 v[218:221], v133 offset:36928
	ds_read_b128 v[222:225], v133 offset:36960
	ds_read_b128 v[226:229], v134 offset:4672
	ds_read_b128 v[230:233], v134 offset:4704
	ds_read_b128 v[234:237], v133 offset:41536
	ds_read_b128 v[238:241], v133 offset:41568
	s_setprio 0
	s_waitcnt lgkmcnt(11)
	v_mfma_f32_32x32x16_bf16 v[0:15], v[176:179], v[168:171], v[0:15]
	s_waitcnt lgkmcnt(10)
	v_mfma_f32_32x32x16_bf16 v[0:15], v[180:183], v[172:175], v[0:15]
	s_waitcnt vmcnt(15)
	ds_write_b128 v132, v[92:95] offset:18432
	global_load_dwordx4 v[92:95], v[158:159], off offset:640
	s_waitcnt lgkmcnt(4)
	v_mfma_f32_32x32x16_bf16 v[0:15], v[226:229], v[218:221], v[0:15]
	s_waitcnt lgkmcnt(3)
	v_mfma_f32_32x32x16_bf16 v[0:15], v[230:233], v[222:225], v[0:15]
	s_waitcnt vmcnt(15)
	ds_write_b128 v132, v[96:99] offset:23040
	global_load_dwordx4 v[96:99], v[160:161], off offset:640
	v_mfma_f32_32x32x16_bf16 v[32:47], v[128:131], v[184:187], v[32:47]
	v_mfma_f32_32x32x16_bf16 v[16:31], v[176:179], v[184:187], v[16:31]
	s_waitcnt vmcnt(15)
	ds_write_b128 v132, v[100:103] offset:27648
	global_load_dwordx4 v[100:103], v[156:157], off offset:640
	v_mfma_f32_32x32x16_bf16 v[32:47], v[146:149], v[188:191], v[32:47]
	v_mfma_f32_32x32x16_bf16 v[16:31], v[180:183], v[188:191], v[16:31]
	s_waitcnt vmcnt(15)
	ds_write_b128 v132, v[104:107] offset:32256
	global_load_dwordx4 v[104:107], v[154:155], off offset:640
	s_waitcnt lgkmcnt(5)
	v_mfma_f32_32x32x16_bf16 v[32:47], v[210:213], v[234:237], v[32:47]
	v_mfma_f32_32x32x16_bf16 v[16:31], v[226:229], v[234:237], v[16:31]
	s_waitcnt vmcnt(15)
	ds_write_b128 v132, v[108:111] offset:55296
	global_load_dwordx4 v[108:111], v[140:141], off offset:640
	s_waitcnt vmcnt(15)
	ds_write_b128 v132, v[112:115] offset:59904
	global_load_dwordx4 v[112:115], v[150:151], off offset:640
	s_waitcnt vmcnt(15)
	ds_write_b128 v132, v[116:119] offset:64512
	global_load_dwordx4 v[116:119], v[152:153], off offset:640
	s_waitcnt vmcnt(15)
	ds_write_b128 v135, v[124:127] offset:13824
	global_load_dwordx4 v[124:127], v[142:143], off offset:640
	s_waitcnt lgkmcnt(0)
	s_barrier
	s_setprio 2
	v_mfma_f32_32x32x16_bf16 v[32:47], v[214:217], v[238:241], v[32:47]
	v_mfma_f32_32x32x16_bf16 v[48:63], v[128:131], v[168:171], v[48:63]
	ds_read_b128 v[128:131], v134 offset:18432
	ds_read_b128 v[168:171], v133 offset:55296
	ds_read_b128 v[176:179], v134 offset:23040
	ds_read_b128 v[180:183], v134 offset:23072
	ds_read_b128 v[184:187], v133 offset:59904
	ds_read_b128 v[188:191], v133 offset:59936
	ds_read_b128 v[226:229], v134 offset:23104
	v_mfma_f32_32x32x16_bf16 v[48:63], v[146:149], v[172:175], v[48:63]
	ds_read_b128 v[146:149], v134 offset:18464
	ds_read_b128 v[172:175], v133 offset:55328
	ds_read_b128 v[234:237], v134 offset:23136
	ds_read_b128 v[242:245], v133 offset:59968
	ds_read_b128 v[246:249], v133 offset:60000
	v_mfma_f32_32x32x16_bf16 v[48:63], v[210:213], v[218:221], v[48:63]
	ds_read_b128 v[210:213], v134 offset:18496
	ds_read_b128 v[218:221], v133 offset:55360
	v_mfma_f32_32x32x16_bf16 v[48:63], v[214:217], v[222:225], v[48:63]
	ds_read_b128 v[214:217], v134 offset:18528
	ds_read_b128 v[222:225], v133 offset:55392
	s_setprio 0
	v_mfma_f32_32x32x16_bf16 v[16:31], v[230:233], v[238:241], v[16:31]
	s_waitcnt lgkmcnt(13)
	v_mfma_f32_32x32x16_bf16 v[0:15], v[176:179], v[168:171], v[0:15]
	s_waitcnt lgkmcnt(7)
	v_mfma_f32_32x32x16_bf16 v[0:15], v[180:183], v[172:175], v[0:15]
	s_waitcnt vmcnt(15)
	ds_write_b128 v132, v[64:67]
	global_load_dwordx4 v[64:67], v[158:159], off offset:768
	s_waitcnt lgkmcnt(3)
	v_mfma_f32_32x32x16_bf16 v[0:15], v[226:229], v[218:221], v[0:15]
	s_waitcnt lgkmcnt(1)
	v_mfma_f32_32x32x16_bf16 v[0:15], v[234:237], v[222:225], v[0:15]
	s_waitcnt vmcnt(15)
	ds_write_b128 v132, v[68:71] offset:4608
	global_load_dwordx4 v[68:71], v[160:161], off offset:768
	v_mfma_f32_32x32x16_bf16 v[48:63], v[128:131], v[168:171], v[48:63]
	v_mfma_f32_32x32x16_bf16 v[32:47], v[128:131], v[184:187], v[32:47]
	s_waitcnt vmcnt(15)
	ds_write_b128 v132, v[72:75] offset:9216
	global_load_dwordx4 v[72:75], v[156:157], off offset:768
	v_mfma_f32_32x32x16_bf16 v[16:31], v[176:179], v[184:187], v[16:31]
	v_mfma_f32_32x32x16_bf16 v[48:63], v[146:149], v[172:175], v[48:63]
	s_waitcnt vmcnt(15)
	ds_write_b128 v132, v[76:79] offset:13824
	global_load_dwordx4 v[76:79], v[154:155], off offset:768
	v_mfma_f32_32x32x16_bf16 v[32:47], v[146:149], v[188:191], v[32:47]
	v_mfma_f32_32x32x16_bf16 v[16:31], v[180:183], v[188:191], v[16:31]
	s_waitcnt vmcnt(15)
	ds_write_b128 v132, v[80:83] offset:36864
	global_load_dwordx4 v[80:83], v[140:141], off offset:768
	v_mfma_f32_32x32x16_bf16 v[48:63], v[210:213], v[218:221], v[48:63]
	v_mfma_f32_32x32x16_bf16 v[32:47], v[210:213], v[242:245], v[32:47]
	s_waitcnt vmcnt(15)
	ds_write_b128 v132, v[84:87] offset:41472
	global_load_dwordx4 v[84:87], v[150:151], off offset:768
	v_mfma_f32_32x32x16_bf16 v[16:31], v[226:229], v[242:245], v[16:31]
	v_mfma_f32_32x32x16_bf16 v[48:63], v[214:217], v[222:225], v[48:63]
	s_waitcnt vmcnt(15)
	ds_write_b128 v132, v[88:91] offset:46080
	global_load_dwordx4 v[88:91], v[152:153], off offset:768
	v_mfma_f32_32x32x16_bf16 v[32:47], v[214:217], v[246:249], v[32:47]
	s_waitcnt vmcnt(15)
	ds_write_b128 v132, v[120:123] offset:50688
	global_load_dwordx4 v[120:123], v[142:143], off offset:768
	s_waitcnt lgkmcnt(0)
	s_barrier
	s_setprio 2
	v_mfma_f32_32x32x16_bf16 v[16:31], v[234:237], v[246:249], v[16:31]
	ds_read_b128 v[128:131], v134
	ds_read_b128 v[146:149], v134 offset:32
	ds_read_b128 v[168:171], v133 offset:36864
	ds_read_b128 v[172:175], v133 offset:36896
	ds_read_b128 v[176:179], v134 offset:4608
	ds_read_b128 v[180:183], v134 offset:4640
	ds_read_b128 v[184:187], v133 offset:41472
	ds_read_b128 v[188:191], v133 offset:41504
	ds_read_b128 v[210:213], v134 offset:64
	ds_read_b128 v[214:217], v134 offset:96
	ds_read_b128 v[218:221], v133 offset:36928
	ds_read_b128 v[222:225], v133 offset:36960
	ds_read_b128 v[226:229], v134 offset:4672
	ds_read_b128 v[230:233], v134 offset:4704
	ds_read_b128 v[234:237], v133 offset:41536
	ds_read_b128 v[238:241], v133 offset:41568
	s_setprio 0
	s_waitcnt lgkmcnt(11)
	v_mfma_f32_32x32x16_bf16 v[0:15], v[176:179], v[168:171], v[0:15]
	s_waitcnt lgkmcnt(10)
	v_mfma_f32_32x32x16_bf16 v[0:15], v[180:183], v[172:175], v[0:15]
	s_waitcnt vmcnt(15)
	ds_write_b128 v132, v[92:95] offset:18432
	global_load_dwordx4 v[92:95], v[158:159], off offset:896
	s_waitcnt lgkmcnt(4)
	v_mfma_f32_32x32x16_bf16 v[0:15], v[226:229], v[218:221], v[0:15]
	s_waitcnt lgkmcnt(3)
	v_mfma_f32_32x32x16_bf16 v[0:15], v[230:233], v[222:225], v[0:15]
	s_waitcnt vmcnt(15)
	ds_write_b128 v132, v[96:99] offset:23040
	global_load_dwordx4 v[96:99], v[160:161], off offset:896
	v_mfma_f32_32x32x16_bf16 v[32:47], v[128:131], v[184:187], v[32:47]
	v_mfma_f32_32x32x16_bf16 v[16:31], v[176:179], v[184:187], v[16:31]
	s_waitcnt vmcnt(15)
	ds_write_b128 v132, v[100:103] offset:27648
	global_load_dwordx4 v[100:103], v[156:157], off offset:896
	v_mfma_f32_32x32x16_bf16 v[32:47], v[146:149], v[188:191], v[32:47]
	v_mfma_f32_32x32x16_bf16 v[16:31], v[180:183], v[188:191], v[16:31]
	s_waitcnt vmcnt(15)
	ds_write_b128 v132, v[104:107] offset:32256
	global_load_dwordx4 v[104:107], v[154:155], off offset:896
	s_waitcnt lgkmcnt(5)
	v_mfma_f32_32x32x16_bf16 v[32:47], v[210:213], v[234:237], v[32:47]
	v_mfma_f32_32x32x16_bf16 v[16:31], v[226:229], v[234:237], v[16:31]
	s_waitcnt vmcnt(15)
	ds_write_b128 v132, v[108:111] offset:55296
	global_load_dwordx4 v[108:111], v[140:141], off offset:896
	s_waitcnt vmcnt(15)
	ds_write_b128 v132, v[112:115] offset:59904
	global_load_dwordx4 v[112:115], v[150:151], off offset:896
	s_waitcnt vmcnt(15)
	ds_write_b128 v132, v[116:119] offset:64512
	global_load_dwordx4 v[116:119], v[152:153], off offset:896
	s_waitcnt vmcnt(15)
	ds_write_b128 v135, v[124:127] offset:13824
	global_load_dwordx4 v[124:127], v[142:143], off offset:896
	s_waitcnt lgkmcnt(0)
	s_barrier
	s_setprio 2
	v_mfma_f32_32x32x16_bf16 v[32:47], v[214:217], v[238:241], v[32:47]
	v_mfma_f32_32x32x16_bf16 v[48:63], v[128:131], v[168:171], v[48:63]
	ds_read_b128 v[128:131], v134 offset:18432
	ds_read_b128 v[140:143], v134 offset:18464
	ds_read_b128 v[150:153], v133 offset:55328
	ds_read_b128 v[154:157], v134 offset:23040
	ds_read_b128 v[158:161], v134 offset:23072
	ds_read_b128 v[168:171], v133 offset:59904
	ds_read_b128 v[176:179], v134 offset:18496
	v_mfma_f32_32x32x16_bf16 v[48:63], v[146:149], v[172:175], v[48:63]
	ds_read_b128 v[146:149], v133 offset:55296
	ds_read_b128 v[172:175], v133 offset:59936
	ds_read_b128 v[180:183], v134 offset:18528
	ds_read_b128 v[184:187], v133 offset:55360
	ds_read_b128 v[188:191], v133 offset:55392
	v_mfma_f32_32x32x16_bf16 v[48:63], v[210:213], v[218:221], v[48:63]
	ds_read_b128 v[210:213], v134 offset:23104
	ds_read_b128 v[218:221], v133 offset:59968
	v_mfma_f32_32x32x16_bf16 v[48:63], v[214:217], v[222:225], v[48:63]
	ds_read_b128 v[214:217], v134 offset:23136
	ds_read_b128 v[222:225], v133 offset:60000
	s_setprio 0
	v_mfma_f32_32x32x16_bf16 v[16:31], v[230:233], v[238:241], v[16:31]
	s_waitcnt lgkmcnt(8)
	v_mfma_f32_32x32x16_bf16 v[0:15], v[154:157], v[146:149], v[0:15]
	v_mfma_f32_32x32x16_bf16 v[0:15], v[158:161], v[150:153], v[0:15]
	s_waitcnt vmcnt(15)
	ds_write_b128 v132, v[64:67]
	s_waitcnt lgkmcnt(4)
	v_mfma_f32_32x32x16_bf16 v[0:15], v[210:213], v[184:187], v[0:15]
	s_waitcnt lgkmcnt(2)
	v_mfma_f32_32x32x16_bf16 v[0:15], v[214:217], v[188:191], v[0:15]
	s_waitcnt vmcnt(14)
	ds_write_b128 v132, v[68:71] offset:4608
	v_mfma_f32_32x32x16_bf16 v[48:63], v[128:131], v[146:149], v[48:63]
	v_mfma_f32_32x32x16_bf16 v[32:47], v[128:131], v[168:171], v[32:47]
	s_waitcnt vmcnt(13)
	ds_write_b128 v132, v[72:75] offset:9216
	v_mfma_f32_32x32x16_bf16 v[16:31], v[154:157], v[168:171], v[16:31]
	v_mfma_f32_32x32x16_bf16 v[48:63], v[140:143], v[150:153], v[48:63]
	s_waitcnt vmcnt(12)
	ds_write_b128 v132, v[76:79] offset:13824
	v_mfma_f32_32x32x16_bf16 v[32:47], v[140:143], v[172:175], v[32:47]
	v_mfma_f32_32x32x16_bf16 v[16:31], v[158:161], v[172:175], v[16:31]
	s_waitcnt vmcnt(11)
	ds_write_b128 v132, v[80:83] offset:36864
	v_mfma_f32_32x32x16_bf16 v[48:63], v[176:179], v[184:187], v[48:63]
	v_mfma_f32_32x32x16_bf16 v[32:47], v[176:179], v[218:221], v[32:47]
	s_waitcnt vmcnt(10)
	ds_write_b128 v132, v[84:87] offset:41472
	v_mfma_f32_32x32x16_bf16 v[16:31], v[210:213], v[218:221], v[16:31]
	v_mfma_f32_32x32x16_bf16 v[48:63], v[180:183], v[188:191], v[48:63]
	s_waitcnt vmcnt(9)
	ds_write_b128 v132, v[88:91] offset:46080
	s_waitcnt lgkmcnt(7)
	v_mfma_f32_32x32x16_bf16 v[32:47], v[180:183], v[222:225], v[32:47]
	s_waitcnt vmcnt(8)
	ds_write_b128 v132, v[120:123] offset:50688
	s_waitcnt lgkmcnt(0)
	s_barrier
	s_setprio 2
	v_mfma_f32_32x32x16_bf16 v[16:31], v[214:217], v[222:225], v[16:31]
	ds_read_b128 v[64:67], v134
	ds_read_b128 v[68:71], v134 offset:32
	ds_read_b128 v[72:75], v133 offset:36864
	ds_read_b128 v[76:79], v133 offset:36896
	ds_read_b128 v[80:83], v134 offset:4608
	ds_read_b128 v[84:87], v134 offset:4640
	ds_read_b128 v[88:91], v133 offset:41472
	ds_read_b128 v[120:123], v133 offset:41504
	ds_read_b128 v[128:131], v134 offset:64
	ds_read_b128 v[140:143], v134 offset:96
	ds_read_b128 v[146:149], v133 offset:36928
	ds_read_b128 v[150:153], v133 offset:36960
	ds_read_b128 v[154:157], v134 offset:4672
	ds_read_b128 v[158:161], v134 offset:4704
	ds_read_b128 v[168:171], v133 offset:41536
	ds_read_b128 v[172:175], v133 offset:41568
	s_setprio 0
	s_waitcnt lgkmcnt(11)
	v_mfma_f32_32x32x16_bf16 v[0:15], v[80:83], v[72:75], v[0:15]
	s_waitcnt lgkmcnt(10)
	v_mfma_f32_32x32x16_bf16 v[0:15], v[84:87], v[76:79], v[0:15]
	s_waitcnt vmcnt(7)
	ds_write_b128 v132, v[92:95] offset:18432
	s_waitcnt lgkmcnt(4)
	v_mfma_f32_32x32x16_bf16 v[0:15], v[154:157], v[146:149], v[0:15]
	s_waitcnt lgkmcnt(3)
	v_mfma_f32_32x32x16_bf16 v[0:15], v[158:161], v[150:153], v[0:15]
	s_waitcnt vmcnt(6)
	ds_write_b128 v132, v[96:99] offset:23040
	v_mfma_f32_32x32x16_bf16 v[32:47], v[64:67], v[88:91], v[32:47]
	v_mfma_f32_32x32x16_bf16 v[16:31], v[80:83], v[88:91], v[16:31]
	s_waitcnt vmcnt(5)
	ds_write_b128 v132, v[100:103] offset:27648
	v_mfma_f32_32x32x16_bf16 v[32:47], v[68:71], v[120:123], v[32:47]
	v_mfma_f32_32x32x16_bf16 v[16:31], v[84:87], v[120:123], v[16:31]
	s_waitcnt vmcnt(4)
	ds_write_b128 v132, v[104:107] offset:32256
	s_waitcnt lgkmcnt(5)
	v_mfma_f32_32x32x16_bf16 v[32:47], v[128:131], v[168:171], v[32:47]
	v_mfma_f32_32x32x16_bf16 v[16:31], v[154:157], v[168:171], v[16:31]
	s_waitcnt vmcnt(3)
	ds_write_b128 v132, v[108:111] offset:55296
	s_waitcnt vmcnt(2)
	ds_write_b128 v132, v[112:115] offset:59904
	s_waitcnt vmcnt(1)
	ds_write_b128 v132, v[116:119] offset:64512
	s_waitcnt vmcnt(0)
	ds_write_b128 v135, v[124:127] offset:13824
	s_waitcnt lgkmcnt(0)
	s_barrier
	s_setprio 2
	v_mfma_f32_32x32x16_bf16 v[32:47], v[140:143], v[172:175], v[32:47]
	v_mfma_f32_32x32x16_bf16 v[48:63], v[64:67], v[72:75], v[48:63]
	ds_read_b128 v[64:67], v134 offset:18432
	ds_read_b128 v[72:75], v133 offset:55296
	ds_read_b128 v[80:83], v134 offset:23040
	ds_read_b128 v[84:87], v134 offset:23072
	ds_read_b128 v[88:91], v133 offset:59904
	ds_read_b128 v[92:95], v133 offset:59936
	ds_read_b128 v[168:171], v133 offset:55360
	v_mfma_f32_32x32x16_bf16 v[48:63], v[68:71], v[76:79], v[48:63]
	ds_read_b128 v[68:71], v134 offset:18464
	ds_read_b128 v[76:79], v133 offset:55328
	ds_read_b128 v[176:179], v133 offset:55392
	ds_read_b128 v[96:99], v134 offset:23104
	ds_read_b128 v[180:183], v134 offset:23136
	ds_read_b128 v[100:103], v133 offset:59968
	ds_read_b128 v[184:187], v133 offset:60000
	v_mfma_f32_32x32x16_bf16 v[48:63], v[128:131], v[146:149], v[48:63]
	ds_read_b128 v[128:131], v134 offset:18496
	ds_read_b128 v[146:149], v134 offset:18528
	s_setprio 0
	v_mfma_f32_32x32x16_bf16 v[48:63], v[140:143], v[150:153], v[48:63]
	v_mfma_f32_32x32x16_bf16 v[16:31], v[158:161], v[172:175], v[16:31]
	s_waitcnt lgkmcnt(13)
	v_mfma_f32_32x32x16_bf16 v[0:15], v[80:83], v[72:75], v[0:15]
	s_waitcnt lgkmcnt(0)
	s_barrier
	v_mfma_f32_32x32x16_bf16 v[0:15], v[84:87], v[76:79], v[0:15]
	v_mfma_f32_32x32x16_bf16 v[0:15], v[96:99], v[168:171], v[0:15]
	v_mfma_f32_32x32x16_bf16 v[0:15], v[180:183], v[176:179], v[0:15]
	v_mfma_f32_32x32x16_bf16 v[32:47], v[64:67], v[88:91], v[32:47]
	v_mfma_f32_32x32x16_bf16 v[16:31], v[80:83], v[88:91], v[16:31]
	v_mfma_f32_32x32x16_bf16 v[32:47], v[68:71], v[92:95], v[32:47]
	v_mfma_f32_32x32x16_bf16 v[16:31], v[84:87], v[92:95], v[16:31]
	v_mfma_f32_32x32x16_bf16 v[32:47], v[128:131], v[100:103], v[32:47]
	v_mfma_f32_32x32x16_bf16 v[16:31], v[96:99], v[100:103], v[16:31]
	v_mfma_f32_32x32x16_bf16 v[32:47], v[146:149], v[184:187], v[32:47]
	v_mfma_f32_32x32x16_bf16 v[48:63], v[64:67], v[72:75], v[48:63]
	v_add_u32_e32 v158, s16, v199
	s_ashr_i32 s9, s8, 31
	v_mov_b64_e32 v[172:173], s[94:95]
	s_lshl_b64 s[20:21], s[8:9], 1
	v_ashrrev_i32_e32 v159, 31, v158
	v_mad_i64_i32 v[82:83], s[24:25], v158, s18, v[172:173]
	v_mfma_f32_32x32x16_bf16 v[48:63], v[68:71], v[76:79], v[48:63]
	v_lshl_add_u64 v[160:161], v[138:139], 0, s[20:21]
	v_lshlrev_b64 v[80:81], 10, v[158:159]
	v_lshl_add_u64 v[82:83], v[82:83], 0, s[20:21]
	v_lshlrev_b32_e32 v144, 1, v136
	v_lshl_add_u64 v[80:81], v[160:161], 0, v[80:81]
	v_lshl_add_u64 v[82:83], v[82:83], 0, v[144:145]
	v_add_co_u32_e32 v82, vcc, s29, v82
	v_mfma_f32_32x32x16_bf16 v[48:63], v[128:131], v[168:171], v[48:63]
	global_load_dwordx4 v[120:123], v[80:81], off
	v_add_u32_e32 v80, 16, v158
	v_addc_co_u32_e32 v83, vcc, 0, v83, vcc
	v_ashrrev_i32_e32 v81, 31, v80
	global_load_dwordx4 v[124:127], v[82:83], off
	v_lshlrev_b64 v[82:83], 10, v[80:81]
	v_mad_i64_i32 v[80:81], s[24:25], v80, s18, v[172:173]
	v_lshl_add_u64 v[82:83], v[160:161], 0, v[82:83]
	v_lshl_add_u64 v[80:81], v[80:81], 0, s[20:21]
	v_add_u32_e32 v156, 32, v158
	v_lshl_add_u64 v[80:81], v[80:81], 0, v[144:145]
	global_load_dwordx4 v[112:115], v[82:83], off
	v_mad_i64_i32 v[82:83], s[24:25], v156, s18, v[172:173]
	v_mfma_f32_32x32x16_bf16 v[48:63], v[146:149], v[176:179], v[48:63]
	v_add_co_u32_e32 v80, vcc, s29, v80
	v_lshl_add_u64 v[82:83], v[82:83], 0, s[20:21]
	s_nop 0
	v_addc_co_u32_e32 v81, vcc, 0, v81, vcc
	v_lshl_add_u64 v[82:83], v[82:83], 0, v[144:145]
	v_add_co_u32_e32 v82, vcc, s29, v82
	v_mfma_f32_32x32x16_bf16 v[16:31], v[180:183], v[184:187], v[16:31]
	s_nop 0
	v_addc_co_u32_e32 v83, vcc, 0, v83, vcc
	v_add_u32_e32 v154, 48, v158
	global_load_dwordx4 v[108:111], v[82:83], off
	v_mad_i64_i32 v[82:83], s[24:25], v154, s18, v[172:173]
	v_lshl_add_u64 v[82:83], v[82:83], 0, s[20:21]
	v_lshl_add_u64 v[82:83], v[82:83], 0, v[144:145]
	v_add_co_u32_e32 v82, vcc, s29, v82
	ds_write2_b32 v164, v48, v32 offset1:32
	v_add_u32_e32 v32, 0x4000, v165
	v_addc_co_u32_e32 v83, vcc, 0, v83, vcc
	v_add_u32_e32 v152, 64, v158
	ds_write2_b32 v32, v0, v16 offset0:128 offset1:160
	v_add_u32_e32 v0, 0x4400, v165
	global_load_dwordx4 v[100:103], v[82:83], off
	v_mad_i64_i32 v[82:83], s[24:25], v152, s18, v[172:173]
	ds_write2_b32 v164, v49, v33 offset0:132 offset1:164
	ds_write2_b32 v0, v1, v17 offset0:4 offset1:36
	v_add_u32_e32 v1, 0x400, v164
	v_lshl_add_u64 v[82:83], v[82:83], 0, s[20:21]
	ds_write2_b32 v1, v50, v34 offset0:8 offset1:40
	ds_write2_b32 v0, v2, v18 offset0:136 offset1:168
	v_add_u32_e32 v0, 0x4800, v165
	v_lshl_add_u64 v[82:83], v[82:83], 0, v[144:145]
	ds_write2_b32 v1, v51, v35 offset0:140 offset1:172
	ds_write2_b32 v0, v3, v19 offset0:12 offset1:44
	v_add_u32_e32 v0, 0x1000, v164
	v_add_u32_e32 v1, 0x5000, v165
	v_add_co_u32_e32 v82, vcc, s29, v82
	ds_write2_b32 v0, v52, v36 offset0:32 offset1:64
	ds_write2_b32 v1, v4, v20 offset0:160 offset1:192
	ds_write2_b32 v0, v53, v37 offset0:164 offset1:196
	v_add_u32_e32 v0, 0x5400, v165
	v_add_u32_e32 v1, 0x1400, v164
	v_addc_co_u32_e32 v83, vcc, 0, v83, vcc
	v_add_u32_e32 v150, 0x50, v158
	ds_write2_b32 v0, v5, v21 offset0:36 offset1:68
	ds_write2_b32 v1, v54, v38 offset0:40 offset1:72
	ds_write2_b32 v0, v6, v22 offset0:168 offset1:200
	v_add_u32_e32 v0, 0x5800, v165
	global_load_dwordx4 v[92:95], v[82:83], off
	v_mad_i64_i32 v[82:83], s[24:25], v150, s18, v[172:173]
	ds_write2_b32 v1, v55, v39 offset0:172 offset1:204
	ds_write2_b32 v0, v7, v23 offset0:44 offset1:76
	v_add_u32_e32 v0, 0x2000, v164
	v_add_u32_e32 v1, 0x6000, v165
	v_lshl_add_u64 v[82:83], v[82:83], 0, s[20:21]
	v_add_u32_e32 v142, 0x60, v158
	ds_write2_b32 v0, v56, v40 offset0:64 offset1:96
	ds_write2_b32 v1, v8, v24 offset0:192 offset1:224
	ds_write2_b32 v0, v57, v41 offset0:196 offset1:228
	v_add_u32_e32 v0, 0x6400, v165
	v_add_u32_e32 v1, 0x2400, v164
	v_lshl_add_u64 v[82:83], v[82:83], 0, v[144:145]
	v_mad_i64_i32 v[66:67], s[24:25], v142, s18, v[172:173]
	ds_write2_b32 v0, v9, v25 offset0:68 offset1:100
	ds_write2_b32 v1, v58, v42 offset0:72 offset1:104
	ds_write2_b32 v0, v10, v26 offset0:200 offset1:232
	v_add_u32_e32 v0, 0x6800, v165
	v_ashrrev_i32_e32 v157, 31, v156
	v_add_co_u32_e32 v84, vcc, s29, v82
	v_lshl_add_u64 v[66:67], v[66:67], 0, s[20:21]
	ds_write2_b32 v1, v59, v43 offset0:204 offset1:236
	ds_write2_b32 v0, v11, v27 offset0:76 offset1:108
	v_add_u32_e32 v0, 0x3000, v164
	global_load_dwordx4 v[116:119], v[80:81], off
	v_lshlrev_b64 v[80:81], 10, v[156:157]
	v_addc_co_u32_e32 v85, vcc, 0, v83, vcc
	v_lshl_add_u64 v[66:67], v[66:67], 0, v[144:145]
	ds_write2_b32 v0, v60, v44 offset0:96 offset1:128
	v_add_u32_e32 v0, 0x7200, v165
	v_lshl_add_u64 v[80:81], v[160:161], 0, v[80:81]
	v_ashrrev_i32_e32 v155, 31, v154
	v_add_co_u32_e32 v66, vcc, s29, v66
	ds_write2_b32 v0, v12, v28 offset0:96 offset1:128
	v_add_u32_e32 v0, 0x3200, v164
	global_load_dwordx4 v[104:107], v[80:81], off
	v_lshlrev_b64 v[80:81], 10, v[154:155]
	v_addc_co_u32_e32 v67, vcc, 0, v67, vcc
	v_add_u32_e32 v140, 0x70, v158
	ds_write2_b32 v0, v61, v45 offset0:100 offset1:132
	v_add_u32_e32 v0, 0x7400, v165
	v_lshl_add_u64 v[80:81], v[160:161], 0, v[80:81]
	v_ashrrev_i32_e32 v153, 31, v152
	v_ashrrev_i32_e32 v143, 31, v142
	global_load_dwordx4 v[76:79], v[66:67], off
	v_mad_i64_i32 v[66:67], s[24:25], v140, s18, v[172:173]
	ds_write2_b32 v0, v13, v29 offset0:100 offset1:132
	v_add_u32_e32 v0, 0x3400, v164
	global_load_dwordx4 v[96:99], v[80:81], off
	v_lshlrev_b64 v[80:81], 10, v[152:153]
	v_lshlrev_b64 v[64:65], 10, v[142:143]
	v_lshl_add_u64 v[66:67], v[66:67], 0, s[20:21]
	ds_write2_b32 v0, v62, v46 offset0:104 offset1:136
	v_add_u32_e32 v0, 0x7600, v165
	v_lshl_add_u64 v[80:81], v[160:161], 0, v[80:81]
	v_ashrrev_i32_e32 v151, 31, v150
	v_lshl_add_u64 v[64:65], v[160:161], 0, v[64:65]
	v_ashrrev_i32_e32 v141, 31, v140
	v_lshl_add_u64 v[66:67], v[66:67], 0, v[144:145]
	ds_write2_b32 v0, v14, v30 offset0:104 offset1:136
	v_add_u32_e32 v0, 0x3600, v164
	v_or_b32_e32 v18, s8, v136
	global_load_dwordx4 v[88:91], v[80:81], off
	v_lshlrev_b64 v[80:81], 10, v[150:151]
	global_load_dwordx4 v[72:75], v[64:65], off
	v_lshlrev_b64 v[64:65], 10, v[140:141]
	v_add_co_u32_e32 v68, vcc, s29, v66
	ds_write2_b32 v0, v63, v47 offset0:108 offset1:140
	v_add_u32_e32 v0, 0x7800, v165
	v_ashrrev_i32_e32 v19, 31, v18
	v_lshl_add_u64 v[80:81], v[160:161], 0, v[80:81]
	v_lshl_add_u64 v[64:65], v[160:161], 0, v[64:65]
	v_addc_co_u32_e32 v69, vcc, 0, v67, vcc
	ds_write2_b32 v0, v15, v31 offset0:108 offset1:140
	v_lshl_add_u64 v[0:1], v[18:19], 2, s[0:1]
	global_load_dwordx4 v[80:83], v[80:81], off
	v_add_u32_e32 v14, v162, v163
	global_load_dwordx4 v[84:87], v[84:85], off
	s_waitcnt vmcnt(13)
	v_lshlrev_b32_e32 v22, 16, v120
	global_load_dwordx4 v[64:67], v[64:65], off
	v_and_b32_e32 v23, 0xffff0000, v120
	global_load_dwordx4 v[68:71], v[68:69], off
	s_waitcnt lgkmcnt(0)
	s_barrier
	global_load_dwordx4 v[2:5], v[0:1], off
	global_load_dwordx4 v[6:9], v[0:1], off offset:16
	ds_read_b128 v[10:13], v14
	ds_read_b128 v[14:17], v14 offset:16
	s_waitcnt vmcnt(15)
	v_lshlrev_b32_e32 v24, 16, v112
	v_and_b32_e32 v25, 0xffff0000, v112
	s_add_i32 s12, s12, s5
	s_add_i32 s10, s10, s11
	s_add_i32 s6, s6, s87
	s_cmpk_gt_i32 s6, 0x2ff
	s_waitcnt vmcnt(1) lgkmcnt(1)
	v_add_f32_e32 v2, v10, v2
	v_add_f32_e32 v3, v11, v3
	v_lshlrev_b32_e32 v10, 16, v124
	v_and_b32_e32 v11, 0xffff0000, v124
	v_mul_f32_e32 v2, 0xbfb8aa3b, v2
	v_mul_f32_e32 v3, 0xbfb8aa3b, v3
	v_mul_f32_e32 v20, 0xbfb8aa3b, v10
	v_mul_f32_e32 v21, 0xbfb8aa3b, v11
	v_exp_f32_e32 v2, v2
	v_exp_f32_e32 v3, v3
	v_exp_f32_e32 v20, v20
	v_exp_f32_e32 v21, v21
	v_add_f32_e32 v2, 1.0, v2
	v_add_f32_e32 v3, 1.0, v3
	v_add_f32_e32 v20, 1.0, v20
	v_add_f32_e32 v21, 1.0, v21
	v_rcp_f32_e32 v2, v2
	v_rcp_f32_e32 v3, v3
	v_rcp_f32_e32 v20, v20
	v_rcp_f32_e32 v21, v21
	v_pk_mul_f32 v[2:3], v[2:3], v[22:23]
	v_pk_mul_f32 v[10:11], v[20:21], v[10:11]
	s_nop 0
	v_pk_mul_f32 v[2:3], v[10:11], v[2:3]
	v_lshlrev_b32_e32 v20, 16, v121
	v_cvt_pk_bf16_f32 v10, v2, v3
	v_add_f32_e32 v2, v12, v4
	v_lshlrev_b32_e32 v4, 16, v125
	v_add_f32_e32 v3, v13, v5
	v_and_b32_e32 v5, 0xffff0000, v125
	v_mul_f32_e32 v11, 0xbfb8aa3b, v4
	v_mul_f32_e32 v2, 0xbfb8aa3b, v2
	v_mul_f32_e32 v3, 0xbfb8aa3b, v3
	v_exp_f32_e32 v11, v11
	v_mul_f32_e32 v12, 0xbfb8aa3b, v5
	v_exp_f32_e32 v2, v2
	v_exp_f32_e32 v3, v3
	v_exp_f32_e32 v13, v12
	v_add_f32_e32 v11, 1.0, v11
	v_add_f32_e32 v2, 1.0, v2
	v_add_f32_e32 v3, 1.0, v3
	v_rcp_f32_e32 v12, v11
	v_add_f32_e32 v11, 1.0, v13
	v_rcp_f32_e32 v2, v2
	v_rcp_f32_e32 v3, v3
	v_rcp_f32_e32 v13, v11
	v_and_b32_e32 v21, 0xffff0000, v121
	v_pk_mul_f32 v[2:3], v[2:3], v[20:21]
	v_pk_mul_f32 v[4:5], v[12:13], v[4:5]
	v_lshlrev_b32_e32 v12, 16, v122
	v_pk_mul_f32 v[2:3], v[4:5], v[2:3]
	v_lshlrev_b32_e32 v4, 16, v126
	v_cvt_pk_bf16_f32 v11, v2, v3
	s_waitcnt vmcnt(0) lgkmcnt(0)
	v_add_f32_e32 v2, v14, v6
	v_add_f32_e32 v3, v15, v7
	v_and_b32_e32 v5, 0xffff0000, v126
	v_mul_f32_e32 v2, 0xbfb8aa3b, v2
	v_mul_f32_e32 v3, 0xbfb8aa3b, v3
	v_mul_f32_e32 v6, 0xbfb8aa3b, v4
	v_mul_f32_e32 v7, 0xbfb8aa3b, v5
	v_exp_f32_e32 v2, v2
	v_exp_f32_e32 v3, v3
	v_exp_f32_e32 v6, v6
	v_exp_f32_e32 v7, v7
	v_add_f32_e32 v2, 1.0, v2
	v_add_f32_e32 v3, 1.0, v3
	v_add_f32_e32 v6, 1.0, v6
	v_add_f32_e32 v7, 1.0, v7
	v_rcp_f32_e32 v2, v2
	v_rcp_f32_e32 v3, v3
	v_rcp_f32_e32 v6, v6
	v_rcp_f32_e32 v7, v7
	v_and_b32_e32 v13, 0xffff0000, v122
	v_pk_mul_f32 v[2:3], v[2:3], v[12:13]
	v_add_u32_e32 v20, s16, v166
	v_pk_mul_f32 v[4:5], v[6:7], v[4:5]
	v_ashrrev_i32_e32 v21, 31, v20
	v_pk_mul_f32 v[2:3], v[4:5], v[2:3]
	v_lshlrev_b32_e32 v4, 16, v127
	v_cvt_pk_bf16_f32 v12, v2, v3
	v_add_f32_e32 v2, v16, v8
	v_add_f32_e32 v3, v17, v9
	v_and_b32_e32 v5, 0xffff0000, v127
	v_mul_f32_e32 v2, 0xbfb8aa3b, v2
	v_mul_f32_e32 v3, 0xbfb8aa3b, v3
	v_mul_f32_e32 v6, 0xbfb8aa3b, v4
	v_mul_f32_e32 v7, 0xbfb8aa3b, v5
	v_exp_f32_e32 v2, v2
	v_exp_f32_e32 v3, v3
	v_exp_f32_e32 v6, v6
	v_exp_f32_e32 v7, v7
	v_add_f32_e32 v2, 1.0, v2
	v_add_f32_e32 v3, 1.0, v3
	v_add_f32_e32 v6, 1.0, v6
	v_add_f32_e32 v7, 1.0, v7
	v_rcp_f32_e32 v2, v2
	v_rcp_f32_e32 v3, v3
	v_rcp_f32_e32 v6, v6
	v_rcp_f32_e32 v7, v7
	v_lshlrev_b32_e32 v8, 16, v123
	v_and_b32_e32 v9, 0xffff0000, v123
	v_pk_mul_f32 v[2:3], v[2:3], v[8:9]
	v_pk_mul_f32 v[4:5], v[6:7], v[4:5]
	s_nop 0
	v_pk_mul_f32 v[2:3], v[4:5], v[2:3]
	s_nop 0
	v_cvt_pk_bf16_f32 v13, v2, v3
	v_lshlrev_b64 v[2:3], 11, v[158:159]
	v_lshl_add_u64 v[4:5], s[94:95], 0, v[2:3]
	v_lshlrev_b64 v[2:3], 1, v[18:19]
	v_lshl_add_u64 v[4:5], v[4:5], 0, v[2:3]
	v_add_co_u32_e32 v4, vcc, s26, v4
	ds_read_b128 v[16:19], v167 offset:16
	s_nop 0
	v_addc_co_u32_e32 v5, vcc, 0, v5, vcc
	global_store_dwordx4 v[4:5], v[10:13], off offset:1024
	global_load_dwordx4 v[4:7], v[0:1], off
	ds_read_b128 v[12:15], v167
	global_load_dwordx4 v[8:11], v[0:1], off offset:16
	s_waitcnt vmcnt(1) lgkmcnt(0)
	v_add_f32_e32 v4, v12, v4
	v_add_f32_e32 v5, v13, v5
	v_lshlrev_b32_e32 v12, 16, v116
	v_and_b32_e32 v13, 0xffff0000, v116
	v_mul_f32_e32 v4, 0xbfb8aa3b, v4
	v_mul_f32_e32 v5, 0xbfb8aa3b, v5
	v_mul_f32_e32 v22, 0xbfb8aa3b, v12
	v_mul_f32_e32 v23, 0xbfb8aa3b, v13
	v_exp_f32_e32 v4, v4
	v_exp_f32_e32 v5, v5
	v_exp_f32_e32 v22, v22
	v_exp_f32_e32 v23, v23
	v_add_f32_e32 v4, 1.0, v4
	v_add_f32_e32 v5, 1.0, v5
	v_add_f32_e32 v22, 1.0, v22
	v_add_f32_e32 v23, 1.0, v23
	v_rcp_f32_e32 v4, v4
	v_rcp_f32_e32 v5, v5
	v_rcp_f32_e32 v22, v22
	v_rcp_f32_e32 v23, v23
	v_pk_mul_f32 v[4:5], v[4:5], v[24:25]
	v_pk_mul_f32 v[12:13], v[22:23], v[12:13]
	s_nop 0
	v_pk_mul_f32 v[4:5], v[12:13], v[4:5]
	v_lshlrev_b32_e32 v12, 16, v117
	v_cvt_pk_bf16_f32 v4, v4, v5
	v_add_f32_e32 v5, v14, v6
	v_mul_f32_e32 v5, 0xbfb8aa3b, v5
	v_add_f32_e32 v6, v15, v7
	v_exp_f32_e32 v5, v5
	v_mul_f32_e32 v6, 0xbfb8aa3b, v6
	v_exp_f32_e32 v7, v6
	v_and_b32_e32 v13, 0xffff0000, v117
	v_add_f32_e32 v5, 1.0, v5
	v_rcp_f32_e32 v6, v5
	v_add_f32_e32 v5, 1.0, v7
	v_mul_f32_e32 v7, 0xbfb8aa3b, v12
	v_exp_f32_e32 v14, v7
	v_mul_f32_e32 v7, 0xbfb8aa3b, v13
	v_exp_f32_e32 v15, v7
	v_rcp_f32_e32 v7, v5
	v_add_f32_e32 v5, 1.0, v14
	v_rcp_f32_e32 v14, v5
	v_add_f32_e32 v5, 1.0, v15
	v_rcp_f32_e32 v15, v5
	v_lshlrev_b32_e32 v22, 16, v113
	v_and_b32_e32 v23, 0xffff0000, v113
	v_pk_mul_f32 v[6:7], v[6:7], v[22:23]
	v_pk_mul_f32 v[12:13], v[14:15], v[12:13]
	v_lshlrev_b32_e32 v14, 16, v114
	v_pk_mul_f32 v[6:7], v[12:13], v[6:7]
	v_and_b32_e32 v15, 0xffff0000, v114
	v_cvt_pk_bf16_f32 v5, v6, v7
	s_waitcnt vmcnt(0)
	v_add_f32_e32 v6, v16, v8
	v_add_f32_e32 v7, v17, v9
	v_lshlrev_b32_e32 v8, 16, v118
	v_and_b32_e32 v9, 0xffff0000, v118
	v_mul_f32_e32 v6, 0xbfb8aa3b, v6
	v_mul_f32_e32 v7, 0xbfb8aa3b, v7
	v_mul_f32_e32 v12, 0xbfb8aa3b, v8
	v_mul_f32_e32 v13, 0xbfb8aa3b, v9
	v_exp_f32_e32 v6, v6
	v_exp_f32_e32 v7, v7
	v_exp_f32_e32 v12, v12
	v_exp_f32_e32 v13, v13
	v_add_f32_e32 v6, 1.0, v6
	v_add_f32_e32 v7, 1.0, v7
	v_add_f32_e32 v12, 1.0, v12
	v_add_f32_e32 v13, 1.0, v13
	v_rcp_f32_e32 v6, v6
	v_rcp_f32_e32 v7, v7
	v_rcp_f32_e32 v12, v12
	v_rcp_f32_e32 v13, v13
	v_lshlrev_b32_e32 v22, 16, v104
	v_pk_mul_f32 v[6:7], v[6:7], v[14:15]
	v_lshlrev_b32_e32 v14, 16, v115
	v_pk_mul_f32 v[8:9], v[12:13], v[8:9]
	v_and_b32_e32 v15, 0xffff0000, v115
	v_pk_mul_f32 v[6:7], v[8:9], v[6:7]
	v_add_f32_e32 v8, v19, v11
	v_cvt_pk_bf16_f32 v6, v6, v7
	v_add_f32_e32 v7, v18, v10
	v_mul_f32_e32 v7, 0xbfb8aa3b, v7
	v_exp_f32_e32 v7, v7
	v_mul_f32_e32 v8, 0xbfb8aa3b, v8
	v_exp_f32_e32 v9, v8
	v_lshlrev_b32_e32 v10, 16, v119
	v_add_f32_e32 v7, 1.0, v7
	v_rcp_f32_e32 v8, v7
	v_add_f32_e32 v7, 1.0, v9
	v_and_b32_e32 v11, 0xffff0000, v119
	v_mul_f32_e32 v9, 0xbfb8aa3b, v10
	v_exp_f32_e32 v12, v9
	v_mul_f32_e32 v9, 0xbfb8aa3b, v11
	v_exp_f32_e32 v13, v9
	v_rcp_f32_e32 v9, v7
	v_add_f32_e32 v7, 1.0, v12
	v_rcp_f32_e32 v12, v7
	v_add_f32_e32 v7, 1.0, v13
	v_rcp_f32_e32 v13, v7
	v_pk_mul_f32 v[8:9], v[8:9], v[14:15]
	v_and_b32_e32 v23, 0xffff0000, v104
	ds_read_b128 v[16:19], v167 offset:8464
	v_pk_mul_f32 v[10:11], v[12:13], v[10:11]
	ds_read_b128 v[12:15], v167 offset:8448
	v_pk_mul_f32 v[8:9], v[10:11], v[8:9]
	s_nop 0
	v_cvt_pk_bf16_f32 v7, v8, v9
	v_lshlrev_b64 v[8:9], 11, v[20:21]
	v_lshl_add_u64 v[8:9], s[94:95], 0, v[8:9]
	v_lshl_add_u64 v[8:9], v[8:9], 0, v[2:3]
	v_add_co_u32_e32 v8, vcc, s26, v8
	s_nop 1
	v_addc_co_u32_e32 v9, vcc, 0, v9, vcc
	global_store_dwordx4 v[8:9], v[4:7], off offset:1024
	global_load_dwordx4 v[4:7], v[0:1], off
	s_nop 0
	global_load_dwordx4 v[8:11], v[0:1], off offset:16
	s_waitcnt vmcnt(1) lgkmcnt(0)
	v_add_f32_e32 v4, v12, v4
	v_add_f32_e32 v5, v13, v5
	v_lshlrev_b32_e32 v12, 16, v108
	v_and_b32_e32 v13, 0xffff0000, v108
	v_mul_f32_e32 v4, 0xbfb8aa3b, v4
	v_mul_f32_e32 v5, 0xbfb8aa3b, v5
	v_mul_f32_e32 v20, 0xbfb8aa3b, v12
	v_mul_f32_e32 v21, 0xbfb8aa3b, v13
	v_exp_f32_e32 v4, v4
	v_exp_f32_e32 v5, v5
	v_exp_f32_e32 v20, v20
	v_exp_f32_e32 v21, v21
	v_add_f32_e32 v4, 1.0, v4
	v_add_f32_e32 v5, 1.0, v5
	v_add_f32_e32 v20, 1.0, v20
	v_add_f32_e32 v21, 1.0, v21
	v_rcp_f32_e32 v4, v4
	v_rcp_f32_e32 v5, v5
	v_rcp_f32_e32 v20, v20
	v_rcp_f32_e32 v21, v21
	v_pk_mul_f32 v[4:5], v[4:5], v[22:23]
	v_lshlrev_b32_e32 v22, 16, v96
	v_pk_mul_f32 v[12:13], v[20:21], v[12:13]
	v_lshlrev_b32_e32 v20, 16, v105
	v_pk_mul_f32 v[4:5], v[12:13], v[4:5]
	v_lshlrev_b32_e32 v12, 16, v109
	v_cvt_pk_bf16_f32 v4, v4, v5
	v_add_f32_e32 v5, v14, v6
	v_mul_f32_e32 v5, 0xbfb8aa3b, v5
	v_add_f32_e32 v6, v15, v7
	v_exp_f32_e32 v5, v5
	v_mul_f32_e32 v6, 0xbfb8aa3b, v6
	v_exp_f32_e32 v7, v6
	v_and_b32_e32 v13, 0xffff0000, v109
	v_add_f32_e32 v5, 1.0, v5
	v_rcp_f32_e32 v6, v5
	v_add_f32_e32 v5, 1.0, v7
	v_mul_f32_e32 v7, 0xbfb8aa3b, v12
	v_exp_f32_e32 v14, v7
	v_mul_f32_e32 v7, 0xbfb8aa3b, v13
	v_exp_f32_e32 v15, v7
	v_rcp_f32_e32 v7, v5
	v_add_f32_e32 v5, 1.0, v14
	v_rcp_f32_e32 v14, v5
	v_add_f32_e32 v5, 1.0, v15
	v_rcp_f32_e32 v15, v5
	v_and_b32_e32 v21, 0xffff0000, v105
	v_pk_mul_f32 v[6:7], v[6:7], v[20:21]
	v_and_b32_e32 v23, 0xffff0000, v96
	v_pk_mul_f32 v[12:13], v[14:15], v[12:13]
	v_lshlrev_b32_e32 v14, 16, v106
	v_pk_mul_f32 v[6:7], v[12:13], v[6:7]
	v_and_b32_e32 v15, 0xffff0000, v106
	v_cvt_pk_bf16_f32 v5, v6, v7
	s_waitcnt vmcnt(0)
	v_add_f32_e32 v6, v16, v8
	v_add_f32_e32 v7, v17, v9
	v_lshlrev_b32_e32 v8, 16, v110
	v_and_b32_e32 v9, 0xffff0000, v110
	v_mul_f32_e32 v6, 0xbfb8aa3b, v6
	v_mul_f32_e32 v7, 0xbfb8aa3b, v7
	v_mul_f32_e32 v12, 0xbfb8aa3b, v8
	v_mul_f32_e32 v13, 0xbfb8aa3b, v9
	v_exp_f32_e32 v6, v6
	v_exp_f32_e32 v7, v7
	v_exp_f32_e32 v12, v12
	v_exp_f32_e32 v13, v13
	v_add_f32_e32 v6, 1.0, v6
	v_add_f32_e32 v7, 1.0, v7
	v_add_f32_e32 v12, 1.0, v12
	v_add_f32_e32 v13, 1.0, v13
	v_rcp_f32_e32 v6, v6
	v_rcp_f32_e32 v7, v7
	v_rcp_f32_e32 v12, v12
	v_rcp_f32_e32 v13, v13
	v_pk_mul_f32 v[6:7], v[6:7], v[14:15]
	v_lshlrev_b32_e32 v14, 16, v107
	v_pk_mul_f32 v[8:9], v[12:13], v[8:9]
	v_and_b32_e32 v15, 0xffff0000, v107
	v_pk_mul_f32 v[6:7], v[8:9], v[6:7]
	v_add_f32_e32 v8, v19, v11
	v_cvt_pk_bf16_f32 v6, v6, v7
	v_add_f32_e32 v7, v18, v10
	v_mul_f32_e32 v7, 0xbfb8aa3b, v7
	v_exp_f32_e32 v7, v7
	v_mul_f32_e32 v8, 0xbfb8aa3b, v8
	v_exp_f32_e32 v9, v8
	v_lshlrev_b32_e32 v10, 16, v111
	v_add_f32_e32 v7, 1.0, v7
	v_rcp_f32_e32 v8, v7
	v_add_f32_e32 v7, 1.0, v9
	v_and_b32_e32 v11, 0xffff0000, v111
	v_mul_f32_e32 v9, 0xbfb8aa3b, v10
	v_exp_f32_e32 v12, v9
	v_mul_f32_e32 v9, 0xbfb8aa3b, v11
	v_exp_f32_e32 v13, v9
	v_rcp_f32_e32 v9, v7
	v_add_f32_e32 v7, 1.0, v12
	v_rcp_f32_e32 v12, v7
	v_add_f32_e32 v7, 1.0, v13
	v_rcp_f32_e32 v13, v7
	v_pk_mul_f32 v[8:9], v[8:9], v[14:15]
	ds_read_b128 v[16:19], v167 offset:16912
	v_pk_mul_f32 v[10:11], v[12:13], v[10:11]
	s_nop 0
	v_pk_mul_f32 v[8:9], v[10:11], v[8:9]
	ds_read_b128 v[12:15], v167 offset:16896
	v_cvt_pk_bf16_f32 v7, v8, v9
	v_lshlrev_b64 v[8:9], 11, v[156:157]
	v_lshl_add_u64 v[8:9], s[94:95], 0, v[8:9]
	v_lshl_add_u64 v[8:9], v[8:9], 0, v[2:3]
	v_add_co_u32_e32 v8, vcc, s26, v8
	s_nop 1
	v_addc_co_u32_e32 v9, vcc, 0, v9, vcc
	global_store_dwordx4 v[8:9], v[4:7], off offset:1024
	global_load_dwordx4 v[4:7], v[0:1], off
	s_nop 0
	global_load_dwordx4 v[8:11], v[0:1], off offset:16
	s_waitcnt vmcnt(1) lgkmcnt(0)
	v_add_f32_e32 v4, v12, v4
	v_add_f32_e32 v5, v13, v5
	v_lshlrev_b32_e32 v12, 16, v100
	v_and_b32_e32 v13, 0xffff0000, v100
	v_mul_f32_e32 v4, 0xbfb8aa3b, v4
	v_mul_f32_e32 v5, 0xbfb8aa3b, v5
	v_mul_f32_e32 v20, 0xbfb8aa3b, v12
	v_mul_f32_e32 v21, 0xbfb8aa3b, v13
	v_exp_f32_e32 v4, v4
	v_exp_f32_e32 v5, v5
	v_exp_f32_e32 v20, v20
	v_exp_f32_e32 v21, v21
	v_add_f32_e32 v4, 1.0, v4
	v_add_f32_e32 v5, 1.0, v5
	v_add_f32_e32 v20, 1.0, v20
	v_add_f32_e32 v21, 1.0, v21
	v_rcp_f32_e32 v4, v4
	v_rcp_f32_e32 v5, v5
	v_rcp_f32_e32 v20, v20
	v_rcp_f32_e32 v21, v21
	v_pk_mul_f32 v[4:5], v[4:5], v[22:23]
	v_lshlrev_b32_e32 v22, 16, v88
	v_pk_mul_f32 v[12:13], v[20:21], v[12:13]
	v_lshlrev_b32_e32 v20, 16, v97
	v_pk_mul_f32 v[4:5], v[12:13], v[4:5]
	v_lshlrev_b32_e32 v12, 16, v101
	v_cvt_pk_bf16_f32 v4, v4, v5
	v_add_f32_e32 v5, v14, v6
	v_mul_f32_e32 v5, 0xbfb8aa3b, v5
	v_add_f32_e32 v6, v15, v7
	v_exp_f32_e32 v5, v5
	v_mul_f32_e32 v6, 0xbfb8aa3b, v6
	v_exp_f32_e32 v7, v6
	v_and_b32_e32 v13, 0xffff0000, v101
	v_add_f32_e32 v5, 1.0, v5
	v_rcp_f32_e32 v6, v5
	v_add_f32_e32 v5, 1.0, v7
	v_mul_f32_e32 v7, 0xbfb8aa3b, v12
	v_exp_f32_e32 v14, v7
	v_mul_f32_e32 v7, 0xbfb8aa3b, v13
	v_exp_f32_e32 v15, v7
	v_rcp_f32_e32 v7, v5
	v_add_f32_e32 v5, 1.0, v14
	v_rcp_f32_e32 v14, v5
	v_add_f32_e32 v5, 1.0, v15
	v_rcp_f32_e32 v15, v5
	v_and_b32_e32 v21, 0xffff0000, v97
	v_pk_mul_f32 v[6:7], v[6:7], v[20:21]
	v_and_b32_e32 v23, 0xffff0000, v88
	v_pk_mul_f32 v[12:13], v[14:15], v[12:13]
	v_lshlrev_b32_e32 v14, 16, v98
	v_pk_mul_f32 v[6:7], v[12:13], v[6:7]
	v_and_b32_e32 v15, 0xffff0000, v98
	v_cvt_pk_bf16_f32 v5, v6, v7
	s_waitcnt vmcnt(0)
	v_add_f32_e32 v6, v16, v8
	v_add_f32_e32 v7, v17, v9
	v_lshlrev_b32_e32 v8, 16, v102
	v_and_b32_e32 v9, 0xffff0000, v102
	v_mul_f32_e32 v6, 0xbfb8aa3b, v6
	v_mul_f32_e32 v7, 0xbfb8aa3b, v7
	v_mul_f32_e32 v12, 0xbfb8aa3b, v8
	v_mul_f32_e32 v13, 0xbfb8aa3b, v9
	v_exp_f32_e32 v6, v6
	v_exp_f32_e32 v7, v7
	v_exp_f32_e32 v12, v12
	v_exp_f32_e32 v13, v13
	v_add_f32_e32 v6, 1.0, v6
	v_add_f32_e32 v7, 1.0, v7
	v_add_f32_e32 v12, 1.0, v12
	v_add_f32_e32 v13, 1.0, v13
	v_rcp_f32_e32 v6, v6
	v_rcp_f32_e32 v7, v7
	v_rcp_f32_e32 v12, v12
	v_rcp_f32_e32 v13, v13
	v_pk_mul_f32 v[6:7], v[6:7], v[14:15]
	v_lshlrev_b32_e32 v14, 16, v99
	v_pk_mul_f32 v[8:9], v[12:13], v[8:9]
	v_and_b32_e32 v15, 0xffff0000, v99
	v_pk_mul_f32 v[6:7], v[8:9], v[6:7]
	v_add_f32_e32 v8, v19, v11
	v_cvt_pk_bf16_f32 v6, v6, v7
	v_add_f32_e32 v7, v18, v10
	v_mul_f32_e32 v7, 0xbfb8aa3b, v7
	v_exp_f32_e32 v7, v7
	v_mul_f32_e32 v8, 0xbfb8aa3b, v8
	v_exp_f32_e32 v9, v8
	v_lshlrev_b32_e32 v10, 16, v103
	v_add_f32_e32 v7, 1.0, v7
	v_rcp_f32_e32 v8, v7
	v_add_f32_e32 v7, 1.0, v9
	v_and_b32_e32 v11, 0xffff0000, v103
	v_mul_f32_e32 v9, 0xbfb8aa3b, v10
	v_exp_f32_e32 v12, v9
	v_mul_f32_e32 v9, 0xbfb8aa3b, v11
	v_exp_f32_e32 v13, v9
	v_rcp_f32_e32 v9, v7
	v_add_f32_e32 v7, 1.0, v12
	v_rcp_f32_e32 v12, v7
	v_add_f32_e32 v7, 1.0, v13
	v_rcp_f32_e32 v13, v7
	v_pk_mul_f32 v[8:9], v[8:9], v[14:15]
	ds_read_b128 v[16:19], v167 offset:25360
	v_pk_mul_f32 v[10:11], v[12:13], v[10:11]
	s_nop 0
	v_pk_mul_f32 v[8:9], v[10:11], v[8:9]
	ds_read_b128 v[12:15], v167 offset:25344
	v_cvt_pk_bf16_f32 v7, v8, v9
	v_lshlrev_b64 v[8:9], 11, v[154:155]
	v_lshl_add_u64 v[8:9], s[94:95], 0, v[8:9]
	v_lshl_add_u64 v[8:9], v[8:9], 0, v[2:3]
	v_add_co_u32_e32 v8, vcc, s26, v8
	s_nop 1
	v_addc_co_u32_e32 v9, vcc, 0, v9, vcc
	global_store_dwordx4 v[8:9], v[4:7], off offset:1024
	global_load_dwordx4 v[4:7], v[0:1], off
	s_nop 0
	global_load_dwordx4 v[8:11], v[0:1], off offset:16
	s_waitcnt vmcnt(1) lgkmcnt(0)
	v_add_f32_e32 v4, v12, v4
	v_add_f32_e32 v5, v13, v5
	v_lshlrev_b32_e32 v12, 16, v92
	v_and_b32_e32 v13, 0xffff0000, v92
	v_mul_f32_e32 v4, 0xbfb8aa3b, v4
	v_mul_f32_e32 v5, 0xbfb8aa3b, v5
	v_mul_f32_e32 v20, 0xbfb8aa3b, v12
	v_mul_f32_e32 v21, 0xbfb8aa3b, v13
	v_exp_f32_e32 v4, v4
	v_exp_f32_e32 v5, v5
	v_exp_f32_e32 v20, v20
	v_exp_f32_e32 v21, v21
	v_add_f32_e32 v4, 1.0, v4
	v_add_f32_e32 v5, 1.0, v5
	v_add_f32_e32 v20, 1.0, v20
	v_add_f32_e32 v21, 1.0, v21
	v_rcp_f32_e32 v4, v4
	v_rcp_f32_e32 v5, v5
	v_rcp_f32_e32 v20, v20
	v_rcp_f32_e32 v21, v21
	v_pk_mul_f32 v[4:5], v[4:5], v[22:23]
	v_lshlrev_b32_e32 v22, 16, v80
	v_pk_mul_f32 v[12:13], v[20:21], v[12:13]
	v_lshlrev_b32_e32 v20, 16, v89
	v_pk_mul_f32 v[4:5], v[12:13], v[4:5]
	v_lshlrev_b32_e32 v12, 16, v93
	v_cvt_pk_bf16_f32 v4, v4, v5
	v_add_f32_e32 v5, v14, v6
	v_mul_f32_e32 v5, 0xbfb8aa3b, v5
	v_add_f32_e32 v6, v15, v7
	v_exp_f32_e32 v5, v5
	v_mul_f32_e32 v6, 0xbfb8aa3b, v6
	v_exp_f32_e32 v7, v6
	v_and_b32_e32 v13, 0xffff0000, v93
	v_add_f32_e32 v5, 1.0, v5
	v_rcp_f32_e32 v6, v5
	v_add_f32_e32 v5, 1.0, v7
	v_mul_f32_e32 v7, 0xbfb8aa3b, v12
	v_exp_f32_e32 v14, v7
	v_mul_f32_e32 v7, 0xbfb8aa3b, v13
	v_exp_f32_e32 v15, v7
	v_rcp_f32_e32 v7, v5
	v_add_f32_e32 v5, 1.0, v14
	v_rcp_f32_e32 v14, v5
	v_add_f32_e32 v5, 1.0, v15
	v_rcp_f32_e32 v15, v5
	v_and_b32_e32 v21, 0xffff0000, v89
	v_pk_mul_f32 v[6:7], v[6:7], v[20:21]
	v_and_b32_e32 v23, 0xffff0000, v80
	v_pk_mul_f32 v[12:13], v[14:15], v[12:13]
	v_lshlrev_b32_e32 v14, 16, v90
	v_pk_mul_f32 v[6:7], v[12:13], v[6:7]
	v_and_b32_e32 v15, 0xffff0000, v90
	v_cvt_pk_bf16_f32 v5, v6, v7
	s_waitcnt vmcnt(0)
	v_add_f32_e32 v6, v16, v8
	v_add_f32_e32 v7, v17, v9
	v_lshlrev_b32_e32 v8, 16, v94
	v_and_b32_e32 v9, 0xffff0000, v94
	v_mul_f32_e32 v6, 0xbfb8aa3b, v6
	v_mul_f32_e32 v7, 0xbfb8aa3b, v7
	v_mul_f32_e32 v12, 0xbfb8aa3b, v8
	v_mul_f32_e32 v13, 0xbfb8aa3b, v9
	v_exp_f32_e32 v6, v6
	v_exp_f32_e32 v7, v7
	v_exp_f32_e32 v12, v12
	v_exp_f32_e32 v13, v13
	v_add_f32_e32 v6, 1.0, v6
	v_add_f32_e32 v7, 1.0, v7
	v_add_f32_e32 v12, 1.0, v12
	v_add_f32_e32 v13, 1.0, v13
	v_rcp_f32_e32 v6, v6
	v_rcp_f32_e32 v7, v7
	v_rcp_f32_e32 v12, v12
	v_rcp_f32_e32 v13, v13
	v_pk_mul_f32 v[6:7], v[6:7], v[14:15]
	v_lshlrev_b32_e32 v14, 16, v91
	v_pk_mul_f32 v[8:9], v[12:13], v[8:9]
	v_and_b32_e32 v15, 0xffff0000, v91
	v_pk_mul_f32 v[6:7], v[8:9], v[6:7]
	v_add_f32_e32 v8, v19, v11
	v_cvt_pk_bf16_f32 v6, v6, v7
	v_add_f32_e32 v7, v18, v10
	v_mul_f32_e32 v7, 0xbfb8aa3b, v7
	v_exp_f32_e32 v7, v7
	v_mul_f32_e32 v8, 0xbfb8aa3b, v8
	v_exp_f32_e32 v9, v8
	v_lshlrev_b32_e32 v10, 16, v95
	v_add_f32_e32 v7, 1.0, v7
	v_rcp_f32_e32 v8, v7
	v_add_f32_e32 v7, 1.0, v9
	v_and_b32_e32 v11, 0xffff0000, v95
	v_mul_f32_e32 v9, 0xbfb8aa3b, v10
	v_exp_f32_e32 v12, v9
	v_mul_f32_e32 v9, 0xbfb8aa3b, v11
	v_exp_f32_e32 v13, v9
	v_rcp_f32_e32 v9, v7
	v_add_f32_e32 v7, 1.0, v12
	v_rcp_f32_e32 v12, v7
	v_add_f32_e32 v7, 1.0, v13
	v_rcp_f32_e32 v13, v7
	v_pk_mul_f32 v[8:9], v[8:9], v[14:15]
	ds_read_b128 v[16:19], v167 offset:33808
	v_pk_mul_f32 v[10:11], v[12:13], v[10:11]
	s_nop 0
	v_pk_mul_f32 v[8:9], v[10:11], v[8:9]
	ds_read_b128 v[12:15], v167 offset:33792
	v_cvt_pk_bf16_f32 v7, v8, v9
	v_lshlrev_b64 v[8:9], 11, v[152:153]
	v_lshl_add_u64 v[8:9], s[94:95], 0, v[8:9]
	v_lshl_add_u64 v[8:9], v[8:9], 0, v[2:3]
	v_add_co_u32_e32 v8, vcc, s26, v8
	s_nop 1
	v_addc_co_u32_e32 v9, vcc, 0, v9, vcc
	global_store_dwordx4 v[8:9], v[4:7], off offset:1024
	global_load_dwordx4 v[4:7], v[0:1], off
	s_nop 0
	global_load_dwordx4 v[8:11], v[0:1], off offset:16
	s_waitcnt vmcnt(1) lgkmcnt(0)
	v_add_f32_e32 v4, v12, v4
	v_add_f32_e32 v5, v13, v5
	v_lshlrev_b32_e32 v12, 16, v84
	v_and_b32_e32 v13, 0xffff0000, v84
	v_mul_f32_e32 v4, 0xbfb8aa3b, v4
	v_mul_f32_e32 v5, 0xbfb8aa3b, v5
	v_mul_f32_e32 v20, 0xbfb8aa3b, v12
	v_mul_f32_e32 v21, 0xbfb8aa3b, v13
	v_exp_f32_e32 v4, v4
	v_exp_f32_e32 v5, v5
	v_exp_f32_e32 v20, v20
	v_exp_f32_e32 v21, v21
	v_add_f32_e32 v4, 1.0, v4
	v_add_f32_e32 v5, 1.0, v5
	v_add_f32_e32 v20, 1.0, v20
	v_add_f32_e32 v21, 1.0, v21
	v_rcp_f32_e32 v4, v4
	v_rcp_f32_e32 v5, v5
	v_rcp_f32_e32 v20, v20
	v_rcp_f32_e32 v21, v21
	v_pk_mul_f32 v[4:5], v[4:5], v[22:23]
	v_lshlrev_b32_e32 v22, 16, v72
	v_pk_mul_f32 v[12:13], v[20:21], v[12:13]
	v_lshlrev_b32_e32 v20, 16, v81
	v_pk_mul_f32 v[4:5], v[12:13], v[4:5]
	v_lshlrev_b32_e32 v12, 16, v85
	v_cvt_pk_bf16_f32 v4, v4, v5
	v_add_f32_e32 v5, v14, v6
	v_mul_f32_e32 v5, 0xbfb8aa3b, v5
	v_add_f32_e32 v6, v15, v7
	v_exp_f32_e32 v5, v5
	v_mul_f32_e32 v6, 0xbfb8aa3b, v6
	v_exp_f32_e32 v7, v6
	v_and_b32_e32 v13, 0xffff0000, v85
	v_add_f32_e32 v5, 1.0, v5
	v_rcp_f32_e32 v6, v5
	v_add_f32_e32 v5, 1.0, v7
	v_mul_f32_e32 v7, 0xbfb8aa3b, v12
	v_exp_f32_e32 v14, v7
	v_mul_f32_e32 v7, 0xbfb8aa3b, v13
	v_exp_f32_e32 v15, v7
	v_rcp_f32_e32 v7, v5
	v_add_f32_e32 v5, 1.0, v14
	v_rcp_f32_e32 v14, v5
	v_add_f32_e32 v5, 1.0, v15
	v_rcp_f32_e32 v15, v5
	v_and_b32_e32 v21, 0xffff0000, v81
	v_pk_mul_f32 v[6:7], v[6:7], v[20:21]
	v_and_b32_e32 v23, 0xffff0000, v72
	v_pk_mul_f32 v[12:13], v[14:15], v[12:13]
	v_lshlrev_b32_e32 v14, 16, v82
	v_pk_mul_f32 v[6:7], v[12:13], v[6:7]
	v_and_b32_e32 v15, 0xffff0000, v82
	v_cvt_pk_bf16_f32 v5, v6, v7
	s_waitcnt vmcnt(0)
	v_add_f32_e32 v6, v16, v8
	v_add_f32_e32 v7, v17, v9
	v_lshlrev_b32_e32 v8, 16, v86
	v_and_b32_e32 v9, 0xffff0000, v86
	v_mul_f32_e32 v6, 0xbfb8aa3b, v6
	v_mul_f32_e32 v7, 0xbfb8aa3b, v7
	v_mul_f32_e32 v12, 0xbfb8aa3b, v8
	v_mul_f32_e32 v13, 0xbfb8aa3b, v9
	v_exp_f32_e32 v6, v6
	v_exp_f32_e32 v7, v7
	v_exp_f32_e32 v12, v12
	v_exp_f32_e32 v13, v13
	v_add_f32_e32 v6, 1.0, v6
	v_add_f32_e32 v7, 1.0, v7
	v_add_f32_e32 v12, 1.0, v12
	v_add_f32_e32 v13, 1.0, v13
	v_rcp_f32_e32 v6, v6
	v_rcp_f32_e32 v7, v7
	v_rcp_f32_e32 v12, v12
	v_rcp_f32_e32 v13, v13
	v_pk_mul_f32 v[6:7], v[6:7], v[14:15]
	v_lshlrev_b32_e32 v14, 16, v83
	v_pk_mul_f32 v[8:9], v[12:13], v[8:9]
	v_and_b32_e32 v15, 0xffff0000, v83
	v_pk_mul_f32 v[6:7], v[8:9], v[6:7]
	v_add_f32_e32 v8, v19, v11
	v_cvt_pk_bf16_f32 v6, v6, v7
	v_add_f32_e32 v7, v18, v10
	v_mul_f32_e32 v7, 0xbfb8aa3b, v7
	v_exp_f32_e32 v7, v7
	v_mul_f32_e32 v8, 0xbfb8aa3b, v8
	v_exp_f32_e32 v9, v8
	v_lshlrev_b32_e32 v10, 16, v87
	v_add_f32_e32 v7, 1.0, v7
	v_rcp_f32_e32 v8, v7
	v_add_f32_e32 v7, 1.0, v9
	v_and_b32_e32 v11, 0xffff0000, v87
	v_mul_f32_e32 v9, 0xbfb8aa3b, v10
	v_exp_f32_e32 v12, v9
	v_mul_f32_e32 v9, 0xbfb8aa3b, v11
	v_exp_f32_e32 v13, v9
	v_rcp_f32_e32 v9, v7
	v_add_f32_e32 v7, 1.0, v12
	v_rcp_f32_e32 v12, v7
	v_add_f32_e32 v7, 1.0, v13
	v_rcp_f32_e32 v13, v7
	v_pk_mul_f32 v[8:9], v[8:9], v[14:15]
	ds_read_b128 v[16:19], v167 offset:42256
	v_pk_mul_f32 v[10:11], v[12:13], v[10:11]
	s_nop 0
	v_pk_mul_f32 v[8:9], v[10:11], v[8:9]
	ds_read_b128 v[12:15], v167 offset:42240
	v_cvt_pk_bf16_f32 v7, v8, v9
	v_lshlrev_b64 v[8:9], 11, v[150:151]
	v_lshl_add_u64 v[8:9], s[94:95], 0, v[8:9]
	v_lshl_add_u64 v[8:9], v[8:9], 0, v[2:3]
	v_add_co_u32_e32 v8, vcc, s26, v8
	s_nop 1
	v_addc_co_u32_e32 v9, vcc, 0, v9, vcc
	global_store_dwordx4 v[8:9], v[4:7], off offset:1024
	global_load_dwordx4 v[4:7], v[0:1], off
	s_nop 0
	global_load_dwordx4 v[8:11], v[0:1], off offset:16
	s_waitcnt vmcnt(1) lgkmcnt(0)
	v_add_f32_e32 v4, v12, v4
	v_add_f32_e32 v5, v13, v5
	v_lshlrev_b32_e32 v12, 16, v76
	v_and_b32_e32 v13, 0xffff0000, v76
	v_mul_f32_e32 v4, 0xbfb8aa3b, v4
	v_mul_f32_e32 v5, 0xbfb8aa3b, v5
	v_mul_f32_e32 v20, 0xbfb8aa3b, v12
	v_mul_f32_e32 v21, 0xbfb8aa3b, v13
	v_exp_f32_e32 v4, v4
	v_exp_f32_e32 v5, v5
	v_exp_f32_e32 v20, v20
	v_exp_f32_e32 v21, v21
	v_add_f32_e32 v4, 1.0, v4
	v_add_f32_e32 v5, 1.0, v5
	v_add_f32_e32 v20, 1.0, v20
	v_add_f32_e32 v21, 1.0, v21
	v_rcp_f32_e32 v4, v4
	v_rcp_f32_e32 v5, v5
	v_rcp_f32_e32 v20, v20
	v_rcp_f32_e32 v21, v21
	v_pk_mul_f32 v[4:5], v[4:5], v[22:23]
	v_pk_mul_f32 v[12:13], v[20:21], v[12:13]
	s_nop 0
	v_pk_mul_f32 v[4:5], v[12:13], v[4:5]
	v_lshlrev_b32_e32 v12, 16, v77
	v_cvt_pk_bf16_f32 v4, v4, v5
	v_add_f32_e32 v5, v14, v6
	v_mul_f32_e32 v5, 0xbfb8aa3b, v5
	v_add_f32_e32 v6, v15, v7
	v_exp_f32_e32 v5, v5
	v_mul_f32_e32 v6, 0xbfb8aa3b, v6
	v_exp_f32_e32 v7, v6
	v_and_b32_e32 v13, 0xffff0000, v77
	v_add_f32_e32 v5, 1.0, v5
	v_rcp_f32_e32 v6, v5
	v_add_f32_e32 v5, 1.0, v7
	v_mul_f32_e32 v7, 0xbfb8aa3b, v12
	v_exp_f32_e32 v14, v7
	v_mul_f32_e32 v7, 0xbfb8aa3b, v13
	v_exp_f32_e32 v15, v7
	v_rcp_f32_e32 v7, v5
	v_add_f32_e32 v5, 1.0, v14
	v_rcp_f32_e32 v14, v5
	v_add_f32_e32 v5, 1.0, v15
	v_rcp_f32_e32 v15, v5
	v_lshlrev_b32_e32 v20, 16, v73
	v_and_b32_e32 v21, 0xffff0000, v73
	v_pk_mul_f32 v[6:7], v[6:7], v[20:21]
	v_pk_mul_f32 v[12:13], v[14:15], v[12:13]
	v_lshlrev_b32_e32 v14, 16, v74
	v_pk_mul_f32 v[6:7], v[12:13], v[6:7]
	v_and_b32_e32 v15, 0xffff0000, v74
	v_cvt_pk_bf16_f32 v5, v6, v7
	s_waitcnt vmcnt(0)
	v_add_f32_e32 v6, v16, v8
	v_add_f32_e32 v7, v17, v9
	v_lshlrev_b32_e32 v8, 16, v78
	v_and_b32_e32 v9, 0xffff0000, v78
	v_mul_f32_e32 v6, 0xbfb8aa3b, v6
	v_mul_f32_e32 v7, 0xbfb8aa3b, v7
	v_mul_f32_e32 v12, 0xbfb8aa3b, v8
	v_mul_f32_e32 v13, 0xbfb8aa3b, v9
	v_exp_f32_e32 v6, v6
	v_exp_f32_e32 v7, v7
	v_exp_f32_e32 v12, v12
	v_exp_f32_e32 v13, v13
	v_add_f32_e32 v6, 1.0, v6
	v_add_f32_e32 v7, 1.0, v7
	v_add_f32_e32 v12, 1.0, v12
	v_add_f32_e32 v13, 1.0, v13
	v_rcp_f32_e32 v6, v6
	v_rcp_f32_e32 v7, v7
	v_rcp_f32_e32 v12, v12
	v_rcp_f32_e32 v13, v13
	v_lshlrev_b32_e32 v20, 16, v64
	v_pk_mul_f32 v[6:7], v[6:7], v[14:15]
	v_lshlrev_b32_e32 v14, 16, v75
	v_pk_mul_f32 v[8:9], v[12:13], v[8:9]
	v_and_b32_e32 v15, 0xffff0000, v75
	v_pk_mul_f32 v[6:7], v[8:9], v[6:7]
	v_add_f32_e32 v8, v19, v11
	v_cvt_pk_bf16_f32 v6, v6, v7
	v_add_f32_e32 v7, v18, v10
	v_mul_f32_e32 v7, 0xbfb8aa3b, v7
	v_exp_f32_e32 v7, v7
	v_mul_f32_e32 v8, 0xbfb8aa3b, v8
	v_exp_f32_e32 v9, v8
	v_lshlrev_b32_e32 v10, 16, v79
	v_add_f32_e32 v7, 1.0, v7
	v_rcp_f32_e32 v8, v7
	v_add_f32_e32 v7, 1.0, v9
	v_and_b32_e32 v11, 0xffff0000, v79
	v_mul_f32_e32 v9, 0xbfb8aa3b, v10
	v_exp_f32_e32 v12, v9
	v_mul_f32_e32 v9, 0xbfb8aa3b, v11
	v_exp_f32_e32 v13, v9
	v_rcp_f32_e32 v9, v7
	v_add_f32_e32 v7, 1.0, v12
	v_rcp_f32_e32 v12, v7
	v_add_f32_e32 v7, 1.0, v13
	v_rcp_f32_e32 v13, v7
	v_pk_mul_f32 v[8:9], v[8:9], v[14:15]
	v_and_b32_e32 v21, 0xffff0000, v64
	ds_read_b128 v[16:19], v167 offset:50704
	v_pk_mul_f32 v[10:11], v[12:13], v[10:11]
	ds_read_b128 v[12:15], v167 offset:50688
	v_pk_mul_f32 v[8:9], v[10:11], v[8:9]
	s_nop 0
	v_cvt_pk_bf16_f32 v7, v8, v9
	v_lshlrev_b64 v[8:9], 11, v[142:143]
	v_lshl_add_u64 v[8:9], s[94:95], 0, v[8:9]
	v_lshl_add_u64 v[8:9], v[8:9], 0, v[2:3]
	v_add_co_u32_e32 v8, vcc, s26, v8
	s_nop 1
	v_addc_co_u32_e32 v9, vcc, 0, v9, vcc
	global_store_dwordx4 v[8:9], v[4:7], off offset:1024
	global_load_dwordx4 v[4:7], v[0:1], off
	s_nop 0
	global_load_dwordx4 v[8:11], v[0:1], off offset:16
	s_waitcnt vmcnt(1) lgkmcnt(0)
	v_add_f32_e32 v0, v12, v4
	v_add_f32_e32 v1, v13, v5
	v_lshlrev_b32_e32 v4, 16, v68
	v_and_b32_e32 v5, 0xffff0000, v68
	v_mul_f32_e32 v0, 0xbfb8aa3b, v0
	v_mul_f32_e32 v1, 0xbfb8aa3b, v1
	v_mul_f32_e32 v12, 0xbfb8aa3b, v4
	v_mul_f32_e32 v13, 0xbfb8aa3b, v5
	v_exp_f32_e32 v0, v0
	v_exp_f32_e32 v1, v1
	v_exp_f32_e32 v12, v12
	v_exp_f32_e32 v13, v13
	v_add_f32_e32 v0, 1.0, v0
	v_add_f32_e32 v1, 1.0, v1
	v_add_f32_e32 v12, 1.0, v12
	v_add_f32_e32 v13, 1.0, v13
	v_rcp_f32_e32 v0, v0
	v_rcp_f32_e32 v1, v1
	v_rcp_f32_e32 v12, v12
	v_rcp_f32_e32 v13, v13
	v_pk_mul_f32 v[0:1], v[0:1], v[20:21]
	v_pk_mul_f32 v[4:5], v[12:13], v[4:5]
	s_nop 0
	v_pk_mul_f32 v[0:1], v[4:5], v[0:1]
	s_nop 0
	v_cvt_pk_bf16_f32 v4, v0, v1
	v_add_f32_e32 v0, v14, v6
	v_lshlrev_b32_e32 v6, 16, v69
	v_add_f32_e32 v1, v15, v7
	v_and_b32_e32 v7, 0xffff0000, v69
	v_mul_f32_e32 v5, 0xbfb8aa3b, v6
	v_mul_f32_e32 v0, 0xbfb8aa3b, v0
	v_mul_f32_e32 v1, 0xbfb8aa3b, v1
	v_exp_f32_e32 v5, v5
	v_mul_f32_e32 v12, 0xbfb8aa3b, v7
	v_exp_f32_e32 v0, v0
	v_exp_f32_e32 v1, v1
	v_exp_f32_e32 v13, v12
	v_add_f32_e32 v5, 1.0, v5
	v_add_f32_e32 v0, 1.0, v0
	v_add_f32_e32 v1, 1.0, v1
	v_rcp_f32_e32 v12, v5
	v_add_f32_e32 v5, 1.0, v13
	v_rcp_f32_e32 v0, v0
	v_rcp_f32_e32 v1, v1
	v_rcp_f32_e32 v13, v5
	v_lshlrev_b32_e32 v14, 16, v65
	v_and_b32_e32 v15, 0xffff0000, v65
	v_pk_mul_f32 v[0:1], v[0:1], v[14:15]
	v_pk_mul_f32 v[6:7], v[12:13], v[6:7]
	v_lshlrev_b32_e32 v12, 16, v66
	v_pk_mul_f32 v[0:1], v[6:7], v[0:1]
	v_lshlrev_b32_e32 v6, 16, v70
	v_cvt_pk_bf16_f32 v5, v0, v1
	s_waitcnt vmcnt(0)
	v_add_f32_e32 v0, v16, v8
	v_add_f32_e32 v1, v17, v9
	v_and_b32_e32 v7, 0xffff0000, v70
	v_mul_f32_e32 v0, 0xbfb8aa3b, v0
	v_mul_f32_e32 v1, 0xbfb8aa3b, v1
	v_mul_f32_e32 v8, 0xbfb8aa3b, v6
	v_mul_f32_e32 v9, 0xbfb8aa3b, v7
	v_exp_f32_e32 v0, v0
	v_exp_f32_e32 v1, v1
	v_exp_f32_e32 v8, v8
	v_exp_f32_e32 v9, v9
	v_add_f32_e32 v0, 1.0, v0
	v_add_f32_e32 v1, 1.0, v1
	v_add_f32_e32 v8, 1.0, v8
	v_add_f32_e32 v9, 1.0, v9
	v_rcp_f32_e32 v0, v0
	v_rcp_f32_e32 v1, v1
	v_rcp_f32_e32 v8, v8
	v_rcp_f32_e32 v9, v9
	v_and_b32_e32 v13, 0xffff0000, v66
	v_pk_mul_f32 v[0:1], v[0:1], v[12:13]
	v_lshlrev_b32_e32 v12, 16, v67
	v_pk_mul_f32 v[6:7], v[8:9], v[6:7]
	v_lshlrev_b32_e32 v8, 16, v71
	v_pk_mul_f32 v[0:1], v[6:7], v[0:1]
	v_and_b32_e32 v9, 0xffff0000, v71
	v_cvt_pk_bf16_f32 v6, v0, v1
	v_add_f32_e32 v0, v18, v10
	v_add_f32_e32 v1, v19, v11
	v_mul_f32_e32 v7, 0xbfb8aa3b, v8
	v_mul_f32_e32 v0, 0xbfb8aa3b, v0
	v_mul_f32_e32 v1, 0xbfb8aa3b, v1
	v_exp_f32_e32 v7, v7
	v_mul_f32_e32 v10, 0xbfb8aa3b, v9
	v_exp_f32_e32 v0, v0
	v_exp_f32_e32 v1, v1
	v_exp_f32_e32 v11, v10
	v_add_f32_e32 v7, 1.0, v7
	v_add_f32_e32 v0, 1.0, v0
	v_add_f32_e32 v1, 1.0, v1
	v_rcp_f32_e32 v10, v7
	v_add_f32_e32 v7, 1.0, v11
	v_rcp_f32_e32 v0, v0
	v_rcp_f32_e32 v1, v1
	v_rcp_f32_e32 v11, v7
	v_and_b32_e32 v13, 0xffff0000, v67
	v_pk_mul_f32 v[0:1], v[0:1], v[12:13]
	v_pk_mul_f32 v[8:9], v[10:11], v[8:9]
	s_nop 0
	v_pk_mul_f32 v[0:1], v[8:9], v[0:1]
	s_nop 0
	v_cvt_pk_bf16_f32 v7, v0, v1
	v_lshlrev_b64 v[0:1], 11, v[140:141]
	v_lshl_add_u64 v[0:1], s[94:95], 0, v[0:1]
	v_lshl_add_u64 v[0:1], v[0:1], 0, v[2:3]
	v_add_co_u32_e32 v0, vcc, 0x1c7e000, v0
	s_nop 1
	v_addc_co_u32_e32 v1, vcc, 0, v1, vcc
	global_store_dwordx4 v[0:1], v[4:7], off offset:1024
	s_barrier
	s_cbranch_scc0 .LBB0_743
	v_mov_b32_e32 v243, 0x13c00

.LBB0_802:
	s_ashr_i32 s0, s6, 31
	s_lshr_b32 s0, s0, 26
	s_add_i32 s0, s6, s0
	s_lshl_b32 s0, s0, 4
	s_and_b32 s1, s0, 0xfffffc00
	s_and_b32 s0, s8, 0x380
	s_or_b32 s10, s1, s0
	v_add_u32_e32 v0, s10, v137
	v_ashrrev_i32_e32 v1, 31, v0
	v_lshlrev_b64 v[0:1], 11, v[0:1]
	v_lshl_add_u64 v[156:157], v[146:147], 0, v[0:1]
	s_sub_i32 s0, s9, s1
	v_add_co_u32_e32 v158, vcc, s25, v156
	s_and_b32 s0, s0, 0xffffff80
	s_nop 0
	v_addc_co_u32_e32 v159, vcc, 0, v157, vcc
	v_add_u32_e32 v0, s0, v137
	v_add_co_u32_e32 v154, vcc, s26, v156
	v_ashrrev_i32_e32 v1, 31, v0
	s_nop 0
	v_addc_co_u32_e32 v155, vcc, 0, v157, vcc
	v_lshlrev_b64 v[0:1], 11, v[0:1]
	v_add_co_u32_e32 v152, vcc, s27, v156
	v_lshl_add_u64 v[138:139], v[190:191], 0, v[0:1]
	s_nop 0
	v_addc_co_u32_e32 v153, vcc, 0, v157, vcc
	v_add_co_u32_e32 v142, vcc, s25, v138
	global_load_dwordx4 v[0:3], v[156:157], off
	s_nop 0
	v_addc_co_u32_e32 v143, vcc, 0, v139, vcc
	v_add_co_u32_e32 v150, vcc, s26, v138
	global_load_dwordx4 v[4:7], v[158:159], off
	s_nop 0
	v_addc_co_u32_e32 v151, vcc, 0, v139, vcc
	v_add_co_u32_e32 v140, vcc, s27, v138
	global_load_dwordx4 v[8:11], v[154:155], off
	s_nop 0
	v_addc_co_u32_e32 v141, vcc, 0, v139, vcc
	global_load_dwordx4 v[12:15], v[152:153], off
	global_load_dwordx4 v[16:19], v[138:139], off
	global_load_dwordx4 v[20:23], v[142:143], off
	global_load_dwordx4 v[24:27], v[150:151], off
	global_load_dwordx4 v[28:31], v[140:141], off
	global_load_dwordx4 v[32:35], v[156:157], off offset:128
	global_load_dwordx4 v[36:39], v[158:159], off offset:128
	global_load_dwordx4 v[48:51], v[152:153], off offset:128
	global_load_dwordx4 v[52:55], v[150:151], off offset:128
	global_load_dwordx4 v[64:67], v[156:157], off offset:256
	global_load_dwordx4 v[68:71], v[158:159], off offset:256
	global_load_dwordx4 v[56:59], v[154:155], off offset:128
	global_load_dwordx4 v[72:75], v[154:155], off offset:256
	global_load_dwordx4 v[76:79], v[152:153], off offset:256
	global_load_dwordx4 v[60:63], v[138:139], off offset:128
	global_load_dwordx4 v[80:83], v[138:139], off offset:256
	global_load_dwordx4 v[112:115], v[142:143], off offset:128
	global_load_dwordx4 v[84:87], v[142:143], off offset:256
	global_load_dwordx4 v[88:91], v[150:151], off offset:256
	global_load_dwordx4 v[124:127], v[140:141], off offset:128
	global_load_dwordx4 v[120:123], v[140:141], off offset:256
	s_waitcnt vmcnt(23)
	ds_write_b128 v132, v[0:3]
	s_waitcnt vmcnt(22)
	ds_write_b128 v132, v[4:7] offset:4608
	s_waitcnt vmcnt(21)
	ds_write_b128 v132, v[8:11] offset:9216
	s_waitcnt vmcnt(20)
	ds_write_b128 v132, v[12:15] offset:13824
	s_waitcnt vmcnt(19)
	ds_write_b128 v132, v[16:19] offset:36864
	s_waitcnt vmcnt(18)
	ds_write_b128 v132, v[20:23] offset:41472
	s_waitcnt vmcnt(17)
	ds_write_b128 v132, v[24:27] offset:46080
	s_waitcnt vmcnt(16)
	ds_write_b128 v132, v[28:31] offset:50688
	s_waitcnt lgkmcnt(0)
	s_barrier
	s_setprio 2
	ds_read_b128 v[166:169], v134
	ds_read_b128 v[170:173], v134 offset:32
	ds_read_b128 v[174:177], v133 offset:36864
	ds_read_b128 v[178:181], v133 offset:36896
	ds_read_b128 v[16:19], v134 offset:4608
	ds_read_b128 v[104:107], v134 offset:4640
	ds_read_b128 v[20:23], v133 offset:41472
	ds_read_b128 v[108:111], v133 offset:41504
	ds_read_b128 v[182:185], v134 offset:64
	ds_read_b128 v[186:189], v134 offset:96
	ds_read_b128 v[208:211], v133 offset:36928
	ds_read_b128 v[212:215], v133 offset:36960
	ds_read_b128 v[116:119], v134 offset:4672
	ds_read_b128 v[216:219], v134 offset:4704
	ds_read_b128 v[220:223], v133 offset:41536
	ds_read_b128 v[224:227], v133 offset:41568
	s_setprio 0
	s_waitcnt lgkmcnt(11)
	v_mfma_f32_32x32x16_bf16 v[0:15], v[16:19], v[174:177], 0
	s_waitcnt lgkmcnt(10)
	v_mfma_f32_32x32x16_bf16 v[0:15], v[104:107], v[178:181], v[0:15]
	s_waitcnt vmcnt(15)
	ds_write_b128 v132, v[32:35] offset:18432
	global_load_dwordx4 v[92:95], v[156:157], off offset:384
	s_waitcnt lgkmcnt(4)
	v_mfma_f32_32x32x16_bf16 v[0:15], v[116:119], v[208:211], v[0:15]
	s_waitcnt lgkmcnt(3)
	v_mfma_f32_32x32x16_bf16 v[0:15], v[216:219], v[212:215], v[0:15]
	s_waitcnt vmcnt(15)
	ds_write_b128 v132, v[36:39] offset:23040
	global_load_dwordx4 v[96:99], v[158:159], off offset:384
	v_mfma_f32_32x32x16_bf16 v[32:47], v[166:169], v[20:23], 0
	v_mfma_f32_32x32x16_bf16 v[16:31], v[16:19], v[20:23], 0
	s_waitcnt vmcnt(11)
	ds_write_b128 v132, v[56:59] offset:27648
	global_load_dwordx4 v[100:103], v[154:155], off offset:384
	v_mfma_f32_32x32x16_bf16 v[32:47], v[170:173], v[108:111], v[32:47]
	v_mfma_f32_32x32x16_bf16 v[16:31], v[104:107], v[108:111], v[16:31]
	ds_write_b128 v132, v[48:51] offset:32256
	global_load_dwordx4 v[104:107], v[152:153], off offset:384
	s_waitcnt lgkmcnt(5)
	v_mfma_f32_32x32x16_bf16 v[32:47], v[182:185], v[220:223], v[32:47]
	v_mfma_f32_32x32x16_bf16 v[16:31], v[116:119], v[220:223], v[16:31]
	s_waitcnt vmcnt(10)
	ds_write_b128 v132, v[60:63] offset:55296
	global_load_dwordx4 v[108:111], v[138:139], off offset:384
	s_waitcnt vmcnt(9)
	ds_write_b128 v132, v[112:115] offset:59904
	global_load_dwordx4 v[112:115], v[142:143], off offset:384
	ds_write_b128 v132, v[52:55] offset:64512
	global_load_dwordx4 v[116:119], v[150:151], off offset:384
	s_waitcnt vmcnt(8)
	ds_write_b128 v135, v[124:127] offset:13824
	global_load_dwordx4 v[124:127], v[140:141], off offset:384
	s_waitcnt lgkmcnt(0)
	s_barrier
	s_setprio 2
	v_mfma_f32_32x32x16_bf16 v[32:47], v[186:189], v[224:227], v[32:47]
	v_mfma_f32_32x32x16_bf16 v[48:63], v[166:169], v[174:177], 0
	ds_read_b128 v[166:169], v134 offset:18432
	ds_read_b128 v[174:177], v133 offset:55296
	ds_read_b128 v[220:223], v133 offset:59904
	ds_read_b128 v[228:231], v133 offset:59936
	ds_read_b128 v[232:235], v133 offset:55360
	ds_read_b128 v[236:239], v133 offset:55392
	ds_read_b128 v[240:243], v134 offset:23104
	v_mfma_f32_32x32x16_bf16 v[48:63], v[170:173], v[178:181], v[48:63]
	ds_read_b128 v[170:173], v134 offset:18464
	ds_read_b128 v[178:181], v133 offset:55328
	ds_read_b128 v[244:247], v134 offset:23136
	ds_read_b128 v[248:251], v133 offset:59968
	ds_read_b128 v[128:131], v133 offset:60000
	v_mfma_f32_32x32x16_bf16 v[48:63], v[182:185], v[208:211], v[48:63]
	ds_read_b128 v[182:185], v134 offset:23040
	ds_read_b128 v[208:211], v134 offset:23072
	v_mfma_f32_32x32x16_bf16 v[48:63], v[186:189], v[212:215], v[48:63]
	ds_read_b128 v[186:189], v134 offset:18496
	ds_read_b128 v[212:215], v134 offset:18528
	s_setprio 0
	v_mfma_f32_32x32x16_bf16 v[16:31], v[216:219], v[224:227], v[16:31]
	s_waitcnt lgkmcnt(3)
	v_mfma_f32_32x32x16_bf16 v[0:15], v[182:185], v[174:177], v[0:15]
	s_waitcnt lgkmcnt(2)
	v_mfma_f32_32x32x16_bf16 v[0:15], v[208:211], v[178:181], v[0:15]
	ds_write_b128 v132, v[64:67]
	global_load_dwordx4 v[64:67], v[156:157], off offset:512
	v_mfma_f32_32x32x16_bf16 v[0:15], v[240:243], v[232:235], v[0:15]
	v_mfma_f32_32x32x16_bf16 v[0:15], v[244:247], v[236:239], v[0:15]
	ds_write_b128 v132, v[68:71] offset:4608
	global_load_dwordx4 v[68:71], v[158:159], off offset:512
	v_mfma_f32_32x32x16_bf16 v[48:63], v[166:169], v[174:177], v[48:63]
	v_mfma_f32_32x32x16_bf16 v[32:47], v[166:169], v[220:223], v[32:47]
	ds_write_b128 v132, v[72:75] offset:9216
	global_load_dwordx4 v[72:75], v[154:155], off offset:512
	v_mfma_f32_32x32x16_bf16 v[16:31], v[182:185], v[220:223], v[16:31]
	v_mfma_f32_32x32x16_bf16 v[48:63], v[170:173], v[178:181], v[48:63]
	ds_write_b128 v132, v[76:79] offset:13824
	global_load_dwordx4 v[76:79], v[152:153], off offset:512
	v_mfma_f32_32x32x16_bf16 v[32:47], v[170:173], v[228:231], v[32:47]
	v_mfma_f32_32x32x16_bf16 v[16:31], v[208:211], v[228:231], v[16:31]
	ds_write_b128 v132, v[80:83] offset:36864
	global_load_dwordx4 v[80:83], v[138:139], off offset:512
	s_waitcnt lgkmcnt(6)
	v_mfma_f32_32x32x16_bf16 v[48:63], v[186:189], v[232:235], v[48:63]
	v_mfma_f32_32x32x16_bf16 v[32:47], v[186:189], v[248:251], v[32:47]
	ds_write_b128 v132, v[84:87] offset:41472
	global_load_dwordx4 v[84:87], v[142:143], off offset:512
	v_mfma_f32_32x32x16_bf16 v[16:31], v[240:243], v[248:251], v[16:31]
	s_waitcnt lgkmcnt(6)
	v_mfma_f32_32x32x16_bf16 v[48:63], v[212:215], v[236:239], v[48:63]
	ds_write_b128 v132, v[88:91] offset:46080
	global_load_dwordx4 v[88:91], v[150:151], off offset:512
	v_mfma_f32_32x32x16_bf16 v[32:47], v[212:215], v[128:131], v[32:47]
	s_waitcnt vmcnt(15)
	ds_write_b128 v132, v[120:123] offset:50688
	global_load_dwordx4 v[120:123], v[140:141], off offset:512
	s_waitcnt lgkmcnt(0)
	s_barrier
	s_setprio 2
	v_mfma_f32_32x32x16_bf16 v[16:31], v[244:247], v[128:131], v[16:31]
	ds_read_b128 v[128:131], v134
	ds_read_b128 v[166:169], v134 offset:32
	ds_read_b128 v[170:173], v133 offset:36864
	ds_read_b128 v[174:177], v133 offset:36896
	ds_read_b128 v[178:181], v134 offset:4608
	ds_read_b128 v[182:185], v134 offset:4640
	ds_read_b128 v[186:189], v133 offset:41472
	ds_read_b128 v[208:211], v133 offset:41504
	ds_read_b128 v[212:215], v134 offset:64
	ds_read_b128 v[216:219], v134 offset:96
	ds_read_b128 v[220:223], v133 offset:36928
	ds_read_b128 v[224:227], v133 offset:36960
	ds_read_b128 v[228:231], v134 offset:4672
	ds_read_b128 v[232:235], v134 offset:4704
	ds_read_b128 v[236:239], v133 offset:41536
	ds_read_b128 v[240:243], v133 offset:41568
	s_setprio 0
	s_waitcnt lgkmcnt(11)
	v_mfma_f32_32x32x16_bf16 v[0:15], v[178:181], v[170:173], v[0:15]
	s_waitcnt lgkmcnt(10)
	v_mfma_f32_32x32x16_bf16 v[0:15], v[182:185], v[174:177], v[0:15]
	s_waitcnt vmcnt(15)
	ds_write_b128 v132, v[92:95] offset:18432
	global_load_dwordx4 v[92:95], v[156:157], off offset:640
	s_waitcnt lgkmcnt(4)
	v_mfma_f32_32x32x16_bf16 v[0:15], v[228:231], v[220:223], v[0:15]
	s_waitcnt lgkmcnt(3)
	v_mfma_f32_32x32x16_bf16 v[0:15], v[232:235], v[224:227], v[0:15]
	s_waitcnt vmcnt(15)
	ds_write_b128 v132, v[96:99] offset:23040
	global_load_dwordx4 v[96:99], v[158:159], off offset:640
	v_mfma_f32_32x32x16_bf16 v[32:47], v[128:131], v[186:189], v[32:47]
	v_mfma_f32_32x32x16_bf16 v[16:31], v[178:181], v[186:189], v[16:31]
	s_waitcnt vmcnt(15)
	ds_write_b128 v132, v[100:103] offset:27648
	global_load_dwordx4 v[100:103], v[154:155], off offset:640
	v_mfma_f32_32x32x16_bf16 v[32:47], v[166:169], v[208:211], v[32:47]
	v_mfma_f32_32x32x16_bf16 v[16:31], v[182:185], v[208:211], v[16:31]
	s_waitcnt vmcnt(15)
	ds_write_b128 v132, v[104:107] offset:32256
	global_load_dwordx4 v[104:107], v[152:153], off offset:640
	s_waitcnt lgkmcnt(5)
	v_mfma_f32_32x32x16_bf16 v[32:47], v[212:215], v[236:239], v[32:47]
	v_mfma_f32_32x32x16_bf16 v[16:31], v[228:231], v[236:239], v[16:31]
	s_waitcnt vmcnt(15)
	ds_write_b128 v132, v[108:111] offset:55296
	global_load_dwordx4 v[108:111], v[138:139], off offset:640
	s_waitcnt vmcnt(15)
	ds_write_b128 v132, v[112:115] offset:59904
	global_load_dwordx4 v[112:115], v[142:143], off offset:640
	s_waitcnt vmcnt(15)
	ds_write_b128 v132, v[116:119] offset:64512
	global_load_dwordx4 v[116:119], v[150:151], off offset:640
	s_waitcnt vmcnt(15)
	ds_write_b128 v135, v[124:127] offset:13824
	global_load_dwordx4 v[124:127], v[140:141], off offset:640
	s_waitcnt lgkmcnt(0)
	s_barrier
	s_setprio 2
	v_mfma_f32_32x32x16_bf16 v[32:47], v[216:219], v[240:243], v[32:47]
	v_mfma_f32_32x32x16_bf16 v[48:63], v[128:131], v[170:173], v[48:63]
	ds_read_b128 v[128:131], v134 offset:18432
	ds_read_b128 v[170:173], v133 offset:55296
	ds_read_b128 v[178:181], v134 offset:23040
	ds_read_b128 v[182:185], v134 offset:23072
	ds_read_b128 v[186:189], v133 offset:59904
	ds_read_b128 v[208:211], v133 offset:59936
	ds_read_b128 v[228:231], v134 offset:23104
	v_mfma_f32_32x32x16_bf16 v[48:63], v[166:169], v[174:177], v[48:63]
	ds_read_b128 v[166:169], v134 offset:18464
	ds_read_b128 v[174:177], v133 offset:55328
	ds_read_b128 v[236:239], v134 offset:23136
	ds_read_b128 v[244:247], v133 offset:59968
	ds_read_b128 v[248:251], v133 offset:60000
	v_mfma_f32_32x32x16_bf16 v[48:63], v[212:215], v[220:223], v[48:63]
	ds_read_b128 v[212:215], v134 offset:18496
	ds_read_b128 v[220:223], v133 offset:55360
	v_mfma_f32_32x32x16_bf16 v[48:63], v[216:219], v[224:227], v[48:63]
	ds_read_b128 v[216:219], v134 offset:18528
	ds_read_b128 v[224:227], v133 offset:55392
	s_setprio 0
	v_mfma_f32_32x32x16_bf16 v[16:31], v[232:235], v[240:243], v[16:31]
	s_waitcnt lgkmcnt(13)
	v_mfma_f32_32x32x16_bf16 v[0:15], v[178:181], v[170:173], v[0:15]
	s_waitcnt lgkmcnt(7)
	v_mfma_f32_32x32x16_bf16 v[0:15], v[182:185], v[174:177], v[0:15]
	s_waitcnt vmcnt(15)
	ds_write_b128 v132, v[64:67]
	global_load_dwordx4 v[64:67], v[156:157], off offset:768
	s_waitcnt lgkmcnt(3)
	v_mfma_f32_32x32x16_bf16 v[0:15], v[228:231], v[220:223], v[0:15]
	s_waitcnt lgkmcnt(1)
	v_mfma_f32_32x32x16_bf16 v[0:15], v[236:239], v[224:227], v[0:15]
	s_waitcnt vmcnt(15)
	ds_write_b128 v132, v[68:71] offset:4608
	global_load_dwordx4 v[68:71], v[158:159], off offset:768
	v_mfma_f32_32x32x16_bf16 v[48:63], v[128:131], v[170:173], v[48:63]
	v_mfma_f32_32x32x16_bf16 v[32:47], v[128:131], v[186:189], v[32:47]
	s_waitcnt vmcnt(15)
	ds_write_b128 v132, v[72:75] offset:9216
	global_load_dwordx4 v[72:75], v[154:155], off offset:768
	v_mfma_f32_32x32x16_bf16 v[16:31], v[178:181], v[186:189], v[16:31]
	v_mfma_f32_32x32x16_bf16 v[48:63], v[166:169], v[174:177], v[48:63]
	s_waitcnt vmcnt(15)
	ds_write_b128 v132, v[76:79] offset:13824
	global_load_dwordx4 v[76:79], v[152:153], off offset:768
	v_mfma_f32_32x32x16_bf16 v[32:47], v[166:169], v[208:211], v[32:47]
	v_mfma_f32_32x32x16_bf16 v[16:31], v[182:185], v[208:211], v[16:31]
	s_waitcnt vmcnt(15)
	ds_write_b128 v132, v[80:83] offset:36864
	global_load_dwordx4 v[80:83], v[138:139], off offset:768
	v_mfma_f32_32x32x16_bf16 v[48:63], v[212:215], v[220:223], v[48:63]
	v_mfma_f32_32x32x16_bf16 v[32:47], v[212:215], v[244:247], v[32:47]
	s_waitcnt vmcnt(15)
	ds_write_b128 v132, v[84:87] offset:41472
	global_load_dwordx4 v[84:87], v[142:143], off offset:768
	v_mfma_f32_32x32x16_bf16 v[16:31], v[228:231], v[244:247], v[16:31]
	v_mfma_f32_32x32x16_bf16 v[48:63], v[216:219], v[224:227], v[48:63]
	s_waitcnt vmcnt(15)
	ds_write_b128 v132, v[88:91] offset:46080
	global_load_dwordx4 v[88:91], v[150:151], off offset:768
	v_mfma_f32_32x32x16_bf16 v[32:47], v[216:219], v[248:251], v[32:47]
	s_waitcnt vmcnt(15)
	ds_write_b128 v132, v[120:123] offset:50688
	global_load_dwordx4 v[120:123], v[140:141], off offset:768
	s_waitcnt lgkmcnt(0)
	s_barrier
	s_setprio 2
	v_mfma_f32_32x32x16_bf16 v[16:31], v[236:239], v[248:251], v[16:31]
	ds_read_b128 v[128:131], v134
	ds_read_b128 v[166:169], v134 offset:32
	ds_read_b128 v[170:173], v133 offset:36864
	ds_read_b128 v[174:177], v133 offset:36896
	ds_read_b128 v[178:181], v134 offset:4608
	ds_read_b128 v[182:185], v134 offset:4640
	ds_read_b128 v[186:189], v133 offset:41472
	ds_read_b128 v[208:211], v133 offset:41504
	ds_read_b128 v[212:215], v134 offset:64
	ds_read_b128 v[216:219], v134 offset:96
	ds_read_b128 v[220:223], v133 offset:36928
	ds_read_b128 v[224:227], v133 offset:36960
	ds_read_b128 v[228:231], v134 offset:4672
	ds_read_b128 v[232:235], v134 offset:4704
	ds_read_b128 v[236:239], v133 offset:41536
	ds_read_b128 v[240:243], v133 offset:41568
	s_setprio 0
	s_waitcnt lgkmcnt(11)
	v_mfma_f32_32x32x16_bf16 v[0:15], v[178:181], v[170:173], v[0:15]
	s_waitcnt lgkmcnt(10)
	v_mfma_f32_32x32x16_bf16 v[0:15], v[182:185], v[174:177], v[0:15]
	s_waitcnt vmcnt(15)
	ds_write_b128 v132, v[92:95] offset:18432
	global_load_dwordx4 v[92:95], v[156:157], off offset:896
	s_waitcnt lgkmcnt(4)
	v_mfma_f32_32x32x16_bf16 v[0:15], v[228:231], v[220:223], v[0:15]
	s_waitcnt lgkmcnt(3)
	v_mfma_f32_32x32x16_bf16 v[0:15], v[232:235], v[224:227], v[0:15]
	s_waitcnt vmcnt(15)
	ds_write_b128 v132, v[96:99] offset:23040
	global_load_dwordx4 v[96:99], v[158:159], off offset:896
	v_mfma_f32_32x32x16_bf16 v[32:47], v[128:131], v[186:189], v[32:47]
	v_mfma_f32_32x32x16_bf16 v[16:31], v[178:181], v[186:189], v[16:31]
	s_waitcnt vmcnt(15)
	ds_write_b128 v132, v[100:103] offset:27648
	global_load_dwordx4 v[100:103], v[154:155], off offset:896
	v_mfma_f32_32x32x16_bf16 v[32:47], v[166:169], v[208:211], v[32:47]
	v_mfma_f32_32x32x16_bf16 v[16:31], v[182:185], v[208:211], v[16:31]
	s_waitcnt vmcnt(15)
	ds_write_b128 v132, v[104:107] offset:32256
	global_load_dwordx4 v[104:107], v[152:153], off offset:896
	s_waitcnt lgkmcnt(5)
	v_mfma_f32_32x32x16_bf16 v[32:47], v[212:215], v[236:239], v[32:47]
	v_mfma_f32_32x32x16_bf16 v[16:31], v[228:231], v[236:239], v[16:31]
	s_waitcnt vmcnt(15)
	ds_write_b128 v132, v[108:111] offset:55296
	global_load_dwordx4 v[108:111], v[138:139], off offset:896
	s_waitcnt vmcnt(15)
	ds_write_b128 v132, v[112:115] offset:59904
	global_load_dwordx4 v[112:115], v[142:143], off offset:896
	s_waitcnt vmcnt(15)
	ds_write_b128 v132, v[116:119] offset:64512
	global_load_dwordx4 v[116:119], v[150:151], off offset:896
	s_waitcnt vmcnt(15)
	ds_write_b128 v135, v[124:127] offset:13824
	global_load_dwordx4 v[124:127], v[140:141], off offset:896
	s_waitcnt lgkmcnt(0)
	s_barrier
	s_setprio 2
	v_mfma_f32_32x32x16_bf16 v[32:47], v[216:219], v[240:243], v[32:47]
	v_mfma_f32_32x32x16_bf16 v[48:63], v[128:131], v[170:173], v[48:63]
	ds_read_b128 v[128:131], v134 offset:18432
	ds_read_b128 v[170:173], v133 offset:55296
	ds_read_b128 v[178:181], v134 offset:23040
	ds_read_b128 v[182:185], v134 offset:23072
	ds_read_b128 v[186:189], v133 offset:59904
	ds_read_b128 v[208:211], v133 offset:59936
	ds_read_b128 v[228:231], v134 offset:23104
	v_mfma_f32_32x32x16_bf16 v[48:63], v[166:169], v[174:177], v[48:63]
	ds_read_b128 v[166:169], v134 offset:18464
	ds_read_b128 v[174:177], v133 offset:55328
	ds_read_b128 v[236:239], v134 offset:23136
	ds_read_b128 v[244:247], v133 offset:59968
	ds_read_b128 v[248:251], v133 offset:60000
	v_mfma_f32_32x32x16_bf16 v[48:63], v[212:215], v[220:223], v[48:63]
	ds_read_b128 v[212:215], v134 offset:18496
	ds_read_b128 v[220:223], v133 offset:55360
	v_mfma_f32_32x32x16_bf16 v[48:63], v[216:219], v[224:227], v[48:63]
	ds_read_b128 v[216:219], v134 offset:18528
	ds_read_b128 v[224:227], v133 offset:55392
	s_setprio 0
	v_mfma_f32_32x32x16_bf16 v[16:31], v[232:235], v[240:243], v[16:31]
	s_waitcnt lgkmcnt(13)
	v_mfma_f32_32x32x16_bf16 v[0:15], v[178:181], v[170:173], v[0:15]
	s_waitcnt lgkmcnt(7)
	v_mfma_f32_32x32x16_bf16 v[0:15], v[182:185], v[174:177], v[0:15]
	s_waitcnt vmcnt(15)
	ds_write_b128 v132, v[64:67]
	global_load_dwordx4 v[64:67], v[156:157], off offset:1024
	s_waitcnt lgkmcnt(3)
	v_mfma_f32_32x32x16_bf16 v[0:15], v[228:231], v[220:223], v[0:15]
	s_waitcnt lgkmcnt(1)
	v_mfma_f32_32x32x16_bf16 v[0:15], v[236:239], v[224:227], v[0:15]
	s_waitcnt vmcnt(15)
	ds_write_b128 v132, v[68:71] offset:4608
	global_load_dwordx4 v[68:71], v[158:159], off offset:1024
	v_mfma_f32_32x32x16_bf16 v[48:63], v[128:131], v[170:173], v[48:63]
	v_mfma_f32_32x32x16_bf16 v[32:47], v[128:131], v[186:189], v[32:47]
	s_waitcnt vmcnt(15)
	ds_write_b128 v132, v[72:75] offset:9216
	global_load_dwordx4 v[72:75], v[154:155], off offset:1024
	v_mfma_f32_32x32x16_bf16 v[16:31], v[178:181], v[186:189], v[16:31]
	v_mfma_f32_32x32x16_bf16 v[48:63], v[166:169], v[174:177], v[48:63]
	s_waitcnt vmcnt(15)
	ds_write_b128 v132, v[76:79] offset:13824
	global_load_dwordx4 v[76:79], v[152:153], off offset:1024
	v_mfma_f32_32x32x16_bf16 v[32:47], v[166:169], v[208:211], v[32:47]
	v_mfma_f32_32x32x16_bf16 v[16:31], v[182:185], v[208:211], v[16:31]
	s_waitcnt vmcnt(15)
	ds_write_b128 v132, v[80:83] offset:36864
	global_load_dwordx4 v[80:83], v[138:139], off offset:1024
	v_mfma_f32_32x32x16_bf16 v[48:63], v[212:215], v[220:223], v[48:63]
	v_mfma_f32_32x32x16_bf16 v[32:47], v[212:215], v[244:247], v[32:47]
	s_waitcnt vmcnt(15)
	ds_write_b128 v132, v[84:87] offset:41472
	global_load_dwordx4 v[84:87], v[142:143], off offset:1024
	v_mfma_f32_32x32x16_bf16 v[16:31], v[228:231], v[244:247], v[16:31]
	v_mfma_f32_32x32x16_bf16 v[48:63], v[216:219], v[224:227], v[48:63]
	s_waitcnt vmcnt(15)
	ds_write_b128 v132, v[88:91] offset:46080
	global_load_dwordx4 v[88:91], v[150:151], off offset:1024
	v_mfma_f32_32x32x16_bf16 v[32:47], v[216:219], v[248:251], v[32:47]
	s_waitcnt vmcnt(15)
	ds_write_b128 v132, v[120:123] offset:50688
	global_load_dwordx4 v[120:123], v[140:141], off offset:1024
	s_waitcnt lgkmcnt(0)
	s_barrier
	s_setprio 2
	v_mfma_f32_32x32x16_bf16 v[16:31], v[236:239], v[248:251], v[16:31]
	ds_read_b128 v[128:131], v134
	ds_read_b128 v[166:169], v134 offset:32
	ds_read_b128 v[170:173], v133 offset:36864
	ds_read_b128 v[174:177], v133 offset:36896
	ds_read_b128 v[178:181], v134 offset:4608
	ds_read_b128 v[182:185], v134 offset:4640
	ds_read_b128 v[186:189], v133 offset:41472
	ds_read_b128 v[208:211], v133 offset:41504
	ds_read_b128 v[212:215], v134 offset:64
	ds_read_b128 v[216:219], v134 offset:96
	ds_read_b128 v[220:223], v133 offset:36928
	ds_read_b128 v[224:227], v133 offset:36960
	ds_read_b128 v[228:231], v134 offset:4672
	ds_read_b128 v[232:235], v134 offset:4704
	ds_read_b128 v[236:239], v133 offset:41536
	ds_read_b128 v[240:243], v133 offset:41568
	s_setprio 0
	s_waitcnt lgkmcnt(11)
	v_mfma_f32_32x32x16_bf16 v[0:15], v[178:181], v[170:173], v[0:15]
	s_waitcnt lgkmcnt(10)
	v_mfma_f32_32x32x16_bf16 v[0:15], v[182:185], v[174:177], v[0:15]
	s_waitcnt vmcnt(15)
	ds_write_b128 v132, v[92:95] offset:18432
	global_load_dwordx4 v[92:95], v[156:157], off offset:1152
	s_waitcnt lgkmcnt(4)
	v_mfma_f32_32x32x16_bf16 v[0:15], v[228:231], v[220:223], v[0:15]
	s_waitcnt lgkmcnt(3)
	v_mfma_f32_32x32x16_bf16 v[0:15], v[232:235], v[224:227], v[0:15]
	s_waitcnt vmcnt(15)
	ds_write_b128 v132, v[96:99] offset:23040
	global_load_dwordx4 v[96:99], v[158:159], off offset:1152
	v_mfma_f32_32x32x16_bf16 v[32:47], v[128:131], v[186:189], v[32:47]
	v_mfma_f32_32x32x16_bf16 v[16:31], v[178:181], v[186:189], v[16:31]
	s_waitcnt vmcnt(15)
	ds_write_b128 v132, v[100:103] offset:27648
	global_load_dwordx4 v[100:103], v[154:155], off offset:1152
	v_mfma_f32_32x32x16_bf16 v[32:47], v[166:169], v[208:211], v[32:47]
	v_mfma_f32_32x32x16_bf16 v[16:31], v[182:185], v[208:211], v[16:31]
	s_waitcnt vmcnt(15)
	ds_write_b128 v132, v[104:107] offset:32256
	global_load_dwordx4 v[104:107], v[152:153], off offset:1152
	s_waitcnt lgkmcnt(5)
	v_mfma_f32_32x32x16_bf16 v[32:47], v[212:215], v[236:239], v[32:47]
	v_mfma_f32_32x32x16_bf16 v[16:31], v[228:231], v[236:239], v[16:31]
	s_waitcnt vmcnt(15)
	ds_write_b128 v132, v[108:111] offset:55296
	global_load_dwordx4 v[108:111], v[138:139], off offset:1152
	s_waitcnt vmcnt(15)
	ds_write_b128 v132, v[112:115] offset:59904
	global_load_dwordx4 v[112:115], v[142:143], off offset:1152
	s_waitcnt vmcnt(15)
	ds_write_b128 v132, v[116:119] offset:64512
	global_load_dwordx4 v[116:119], v[150:151], off offset:1152
	s_waitcnt vmcnt(15)
	ds_write_b128 v135, v[124:127] offset:13824
	global_load_dwordx4 v[124:127], v[140:141], off offset:1152
	s_waitcnt lgkmcnt(0)
	s_barrier
	s_setprio 2
	v_mfma_f32_32x32x16_bf16 v[32:47], v[216:219], v[240:243], v[32:47]
	v_mfma_f32_32x32x16_bf16 v[48:63], v[128:131], v[170:173], v[48:63]
	ds_read_b128 v[128:131], v134 offset:18432
	ds_read_b128 v[170:173], v133 offset:55296
	ds_read_b128 v[178:181], v134 offset:23040
	ds_read_b128 v[182:185], v134 offset:23072
	ds_read_b128 v[186:189], v133 offset:59904
	ds_read_b128 v[208:211], v133 offset:59936
	ds_read_b128 v[228:231], v134 offset:23104
	v_mfma_f32_32x32x16_bf16 v[48:63], v[166:169], v[174:177], v[48:63]
	ds_read_b128 v[166:169], v134 offset:18464
	ds_read_b128 v[174:177], v133 offset:55328
	ds_read_b128 v[236:239], v134 offset:23136
	ds_read_b128 v[244:247], v133 offset:59968
	ds_read_b128 v[248:251], v133 offset:60000
	v_mfma_f32_32x32x16_bf16 v[48:63], v[212:215], v[220:223], v[48:63]
	ds_read_b128 v[212:215], v134 offset:18496
	ds_read_b128 v[220:223], v133 offset:55360
	v_mfma_f32_32x32x16_bf16 v[48:63], v[216:219], v[224:227], v[48:63]
	ds_read_b128 v[216:219], v134 offset:18528
	ds_read_b128 v[224:227], v133 offset:55392
	s_setprio 0
	v_mfma_f32_32x32x16_bf16 v[16:31], v[232:235], v[240:243], v[16:31]
	s_waitcnt lgkmcnt(13)
	v_mfma_f32_32x32x16_bf16 v[0:15], v[178:181], v[170:173], v[0:15]
	s_waitcnt lgkmcnt(7)
	v_mfma_f32_32x32x16_bf16 v[0:15], v[182:185], v[174:177], v[0:15]
	s_waitcnt vmcnt(15)
	ds_write_b128 v132, v[64:67]
	global_load_dwordx4 v[64:67], v[156:157], off offset:1280
	s_waitcnt lgkmcnt(3)
	v_mfma_f32_32x32x16_bf16 v[0:15], v[228:231], v[220:223], v[0:15]
	s_waitcnt lgkmcnt(1)
	v_mfma_f32_32x32x16_bf16 v[0:15], v[236:239], v[224:227], v[0:15]
	s_waitcnt vmcnt(15)
	ds_write_b128 v132, v[68:71] offset:4608
	global_load_dwordx4 v[68:71], v[158:159], off offset:1280
	v_mfma_f32_32x32x16_bf16 v[48:63], v[128:131], v[170:173], v[48:63]
	v_mfma_f32_32x32x16_bf16 v[32:47], v[128:131], v[186:189], v[32:47]
	s_waitcnt vmcnt(15)
	ds_write_b128 v132, v[72:75] offset:9216
	global_load_dwordx4 v[72:75], v[154:155], off offset:1280
	v_mfma_f32_32x32x16_bf16 v[16:31], v[178:181], v[186:189], v[16:31]
	v_mfma_f32_32x32x16_bf16 v[48:63], v[166:169], v[174:177], v[48:63]
	s_waitcnt vmcnt(15)
	ds_write_b128 v132, v[76:79] offset:13824
	global_load_dwordx4 v[76:79], v[152:153], off offset:1280
	v_mfma_f32_32x32x16_bf16 v[32:47], v[166:169], v[208:211], v[32:47]
	v_mfma_f32_32x32x16_bf16 v[16:31], v[182:185], v[208:211], v[16:31]
	s_waitcnt vmcnt(15)
	ds_write_b128 v132, v[80:83] offset:36864
	global_load_dwordx4 v[80:83], v[138:139], off offset:1280
	v_mfma_f32_32x32x16_bf16 v[48:63], v[212:215], v[220:223], v[48:63]
	v_mfma_f32_32x32x16_bf16 v[32:47], v[212:215], v[244:247], v[32:47]
	s_waitcnt vmcnt(15)
	ds_write_b128 v132, v[84:87] offset:41472
	global_load_dwordx4 v[84:87], v[142:143], off offset:1280
	v_mfma_f32_32x32x16_bf16 v[16:31], v[228:231], v[244:247], v[16:31]
	v_mfma_f32_32x32x16_bf16 v[48:63], v[216:219], v[224:227], v[48:63]
	s_waitcnt vmcnt(15)
	ds_write_b128 v132, v[88:91] offset:46080
	global_load_dwordx4 v[88:91], v[150:151], off offset:1280
	v_mfma_f32_32x32x16_bf16 v[32:47], v[216:219], v[248:251], v[32:47]
	s_waitcnt vmcnt(15)
	ds_write_b128 v132, v[120:123] offset:50688
	global_load_dwordx4 v[120:123], v[140:141], off offset:1280
	s_waitcnt lgkmcnt(0)
	s_barrier
	s_setprio 2
	v_mfma_f32_32x32x16_bf16 v[16:31], v[236:239], v[248:251], v[16:31]
	ds_read_b128 v[128:131], v134
	ds_read_b128 v[166:169], v134 offset:32
	ds_read_b128 v[170:173], v133 offset:36864
	ds_read_b128 v[174:177], v133 offset:36896
	ds_read_b128 v[178:181], v134 offset:4608
	ds_read_b128 v[182:185], v134 offset:4640
	ds_read_b128 v[186:189], v133 offset:41472
	ds_read_b128 v[208:211], v133 offset:41504
	ds_read_b128 v[212:215], v134 offset:64
	ds_read_b128 v[216:219], v134 offset:96
	ds_read_b128 v[220:223], v133 offset:36928
	ds_read_b128 v[224:227], v133 offset:36960
	ds_read_b128 v[228:231], v134 offset:4672
	ds_read_b128 v[232:235], v134 offset:4704
	ds_read_b128 v[236:239], v133 offset:41536
	ds_read_b128 v[240:243], v133 offset:41568
	s_setprio 0
	s_waitcnt lgkmcnt(11)
	v_mfma_f32_32x32x16_bf16 v[0:15], v[178:181], v[170:173], v[0:15]
	s_waitcnt lgkmcnt(10)
	v_mfma_f32_32x32x16_bf16 v[0:15], v[182:185], v[174:177], v[0:15]
	s_waitcnt vmcnt(15)
	ds_write_b128 v132, v[92:95] offset:18432
	global_load_dwordx4 v[92:95], v[156:157], off offset:1408
	s_waitcnt lgkmcnt(4)
	v_mfma_f32_32x32x16_bf16 v[0:15], v[228:231], v[220:223], v[0:15]
	s_waitcnt lgkmcnt(3)
	v_mfma_f32_32x32x16_bf16 v[0:15], v[232:235], v[224:227], v[0:15]
	s_waitcnt vmcnt(15)
	ds_write_b128 v132, v[96:99] offset:23040
	global_load_dwordx4 v[96:99], v[158:159], off offset:1408
	v_mfma_f32_32x32x16_bf16 v[32:47], v[128:131], v[186:189], v[32:47]
	v_mfma_f32_32x32x16_bf16 v[16:31], v[178:181], v[186:189], v[16:31]
	s_waitcnt vmcnt(15)
	ds_write_b128 v132, v[100:103] offset:27648
	global_load_dwordx4 v[100:103], v[154:155], off offset:1408
	v_mfma_f32_32x32x16_bf16 v[32:47], v[166:169], v[208:211], v[32:47]
	v_mfma_f32_32x32x16_bf16 v[16:31], v[182:185], v[208:211], v[16:31]
	s_waitcnt vmcnt(15)
	ds_write_b128 v132, v[104:107] offset:32256
	global_load_dwordx4 v[104:107], v[152:153], off offset:1408
	s_waitcnt lgkmcnt(5)
	v_mfma_f32_32x32x16_bf16 v[32:47], v[212:215], v[236:239], v[32:47]
	v_mfma_f32_32x32x16_bf16 v[16:31], v[228:231], v[236:239], v[16:31]
	s_waitcnt vmcnt(15)
	ds_write_b128 v132, v[108:111] offset:55296
	global_load_dwordx4 v[108:111], v[138:139], off offset:1408
	s_waitcnt vmcnt(15)
	ds_write_b128 v132, v[112:115] offset:59904
	global_load_dwordx4 v[112:115], v[142:143], off offset:1408
	s_waitcnt vmcnt(15)
	ds_write_b128 v132, v[116:119] offset:64512
	global_load_dwordx4 v[116:119], v[150:151], off offset:1408
	s_waitcnt vmcnt(15)
	ds_write_b128 v135, v[124:127] offset:13824
	global_load_dwordx4 v[124:127], v[140:141], off offset:1408
	s_waitcnt lgkmcnt(0)
	s_barrier
	s_setprio 2
	v_mfma_f32_32x32x16_bf16 v[32:47], v[216:219], v[240:243], v[32:47]
	v_mfma_f32_32x32x16_bf16 v[48:63], v[128:131], v[170:173], v[48:63]
	ds_read_b128 v[128:131], v134 offset:18432
	ds_read_b128 v[170:173], v133 offset:55296
	ds_read_b128 v[178:181], v134 offset:23040
	ds_read_b128 v[182:185], v134 offset:23072
	ds_read_b128 v[186:189], v133 offset:59904
	ds_read_b128 v[208:211], v133 offset:59936
	ds_read_b128 v[228:231], v134 offset:23104
	v_mfma_f32_32x32x16_bf16 v[48:63], v[166:169], v[174:177], v[48:63]
	ds_read_b128 v[166:169], v134 offset:18464
	ds_read_b128 v[174:177], v133 offset:55328
	ds_read_b128 v[236:239], v134 offset:23136
	ds_read_b128 v[244:247], v133 offset:59968
	ds_read_b128 v[248:251], v133 offset:60000
	v_mfma_f32_32x32x16_bf16 v[48:63], v[212:215], v[220:223], v[48:63]
	ds_read_b128 v[212:215], v134 offset:18496
	ds_read_b128 v[220:223], v133 offset:55360
	v_mfma_f32_32x32x16_bf16 v[48:63], v[216:219], v[224:227], v[48:63]
	ds_read_b128 v[216:219], v134 offset:18528
	ds_read_b128 v[224:227], v133 offset:55392
	s_setprio 0
	v_mfma_f32_32x32x16_bf16 v[16:31], v[232:235], v[240:243], v[16:31]
	s_waitcnt lgkmcnt(13)
	v_mfma_f32_32x32x16_bf16 v[0:15], v[178:181], v[170:173], v[0:15]
	s_waitcnt lgkmcnt(7)
	v_mfma_f32_32x32x16_bf16 v[0:15], v[182:185], v[174:177], v[0:15]
	s_waitcnt vmcnt(15)
	ds_write_b128 v132, v[64:67]
	global_load_dwordx4 v[64:67], v[156:157], off offset:1536
	s_waitcnt lgkmcnt(3)
	v_mfma_f32_32x32x16_bf16 v[0:15], v[228:231], v[220:223], v[0:15]
	s_waitcnt lgkmcnt(1)
	v_mfma_f32_32x32x16_bf16 v[0:15], v[236:239], v[224:227], v[0:15]
	s_waitcnt vmcnt(15)
	ds_write_b128 v132, v[68:71] offset:4608
	global_load_dwordx4 v[68:71], v[158:159], off offset:1536
	v_mfma_f32_32x32x16_bf16 v[48:63], v[128:131], v[170:173], v[48:63]
	v_mfma_f32_32x32x16_bf16 v[32:47], v[128:131], v[186:189], v[32:47]
	s_waitcnt vmcnt(15)
	ds_write_b128 v132, v[72:75] offset:9216
	global_load_dwordx4 v[72:75], v[154:155], off offset:1536
	v_mfma_f32_32x32x16_bf16 v[16:31], v[178:181], v[186:189], v[16:31]
	v_mfma_f32_32x32x16_bf16 v[48:63], v[166:169], v[174:177], v[48:63]
	s_waitcnt vmcnt(15)
	ds_write_b128 v132, v[76:79] offset:13824
	global_load_dwordx4 v[76:79], v[152:153], off offset:1536
	v_mfma_f32_32x32x16_bf16 v[32:47], v[166:169], v[208:211], v[32:47]
	v_mfma_f32_32x32x16_bf16 v[16:31], v[182:185], v[208:211], v[16:31]
	s_waitcnt vmcnt(15)
	ds_write_b128 v132, v[80:83] offset:36864
	global_load_dwordx4 v[80:83], v[138:139], off offset:1536
	v_mfma_f32_32x32x16_bf16 v[48:63], v[212:215], v[220:223], v[48:63]
	v_mfma_f32_32x32x16_bf16 v[32:47], v[212:215], v[244:247], v[32:47]
	s_waitcnt vmcnt(15)
	ds_write_b128 v132, v[84:87] offset:41472
	global_load_dwordx4 v[84:87], v[142:143], off offset:1536
	v_mfma_f32_32x32x16_bf16 v[16:31], v[228:231], v[244:247], v[16:31]
	v_mfma_f32_32x32x16_bf16 v[48:63], v[216:219], v[224:227], v[48:63]
	s_waitcnt vmcnt(15)
	ds_write_b128 v132, v[88:91] offset:46080
	global_load_dwordx4 v[88:91], v[150:151], off offset:1536
	v_mfma_f32_32x32x16_bf16 v[32:47], v[216:219], v[248:251], v[32:47]
	s_waitcnt vmcnt(15)
	ds_write_b128 v132, v[120:123] offset:50688
	global_load_dwordx4 v[120:123], v[140:141], off offset:1536
	s_waitcnt lgkmcnt(0)
	s_barrier
	s_setprio 2
	v_mfma_f32_32x32x16_bf16 v[16:31], v[236:239], v[248:251], v[16:31]
	ds_read_b128 v[128:131], v134
	ds_read_b128 v[166:169], v134 offset:32
	ds_read_b128 v[170:173], v133 offset:36864
	ds_read_b128 v[174:177], v133 offset:36896
	ds_read_b128 v[178:181], v134 offset:4608
	ds_read_b128 v[182:185], v134 offset:4640
	ds_read_b128 v[186:189], v133 offset:41472
	ds_read_b128 v[208:211], v133 offset:41504
	ds_read_b128 v[212:215], v134 offset:64
	ds_read_b128 v[216:219], v134 offset:96
	ds_read_b128 v[220:223], v133 offset:36928
	ds_read_b128 v[224:227], v133 offset:36960
	ds_read_b128 v[228:231], v134 offset:4672
	ds_read_b128 v[232:235], v134 offset:4704
	ds_read_b128 v[236:239], v133 offset:41536
	ds_read_b128 v[240:243], v133 offset:41568
	s_setprio 0
	s_waitcnt lgkmcnt(11)
	v_mfma_f32_32x32x16_bf16 v[0:15], v[178:181], v[170:173], v[0:15]
	s_waitcnt lgkmcnt(10)
	v_mfma_f32_32x32x16_bf16 v[0:15], v[182:185], v[174:177], v[0:15]
	s_waitcnt vmcnt(15)
	ds_write_b128 v132, v[92:95] offset:18432
	global_load_dwordx4 v[92:95], v[156:157], off offset:1664
	s_waitcnt lgkmcnt(4)
	v_mfma_f32_32x32x16_bf16 v[0:15], v[228:231], v[220:223], v[0:15]
	s_waitcnt lgkmcnt(3)
	v_mfma_f32_32x32x16_bf16 v[0:15], v[232:235], v[224:227], v[0:15]
	s_waitcnt vmcnt(15)
	ds_write_b128 v132, v[96:99] offset:23040
	global_load_dwordx4 v[96:99], v[158:159], off offset:1664
	v_mfma_f32_32x32x16_bf16 v[32:47], v[128:131], v[186:189], v[32:47]
	v_mfma_f32_32x32x16_bf16 v[16:31], v[178:181], v[186:189], v[16:31]
	s_waitcnt vmcnt(15)
	ds_write_b128 v132, v[100:103] offset:27648
	global_load_dwordx4 v[100:103], v[154:155], off offset:1664
	v_mfma_f32_32x32x16_bf16 v[32:47], v[166:169], v[208:211], v[32:47]
	v_mfma_f32_32x32x16_bf16 v[16:31], v[182:185], v[208:211], v[16:31]
	s_waitcnt vmcnt(15)
	ds_write_b128 v132, v[104:107] offset:32256
	global_load_dwordx4 v[104:107], v[152:153], off offset:1664
	s_waitcnt lgkmcnt(5)
	v_mfma_f32_32x32x16_bf16 v[32:47], v[212:215], v[236:239], v[32:47]
	v_mfma_f32_32x32x16_bf16 v[16:31], v[228:231], v[236:239], v[16:31]
	s_waitcnt vmcnt(15)
	ds_write_b128 v132, v[108:111] offset:55296
	global_load_dwordx4 v[108:111], v[138:139], off offset:1664
	s_waitcnt vmcnt(15)
	ds_write_b128 v132, v[112:115] offset:59904
	global_load_dwordx4 v[112:115], v[142:143], off offset:1664
	s_waitcnt vmcnt(15)
	ds_write_b128 v132, v[116:119] offset:64512
	global_load_dwordx4 v[116:119], v[150:151], off offset:1664
	s_waitcnt vmcnt(15)
	ds_write_b128 v135, v[124:127] offset:13824
	global_load_dwordx4 v[124:127], v[140:141], off offset:1664
	s_waitcnt lgkmcnt(0)
	s_barrier
	s_setprio 2
	v_mfma_f32_32x32x16_bf16 v[32:47], v[216:219], v[240:243], v[32:47]
	v_mfma_f32_32x32x16_bf16 v[48:63], v[128:131], v[170:173], v[48:63]
	ds_read_b128 v[128:131], v134 offset:18432
	ds_read_b128 v[170:173], v133 offset:55296
	ds_read_b128 v[178:181], v134 offset:23040
	ds_read_b128 v[182:185], v134 offset:23072
	ds_read_b128 v[186:189], v133 offset:59904
	ds_read_b128 v[208:211], v133 offset:59936
	ds_read_b128 v[228:231], v134 offset:23104
	v_mfma_f32_32x32x16_bf16 v[48:63], v[166:169], v[174:177], v[48:63]
	ds_read_b128 v[166:169], v134 offset:18464
	ds_read_b128 v[174:177], v133 offset:55328
	ds_read_b128 v[236:239], v134 offset:23136
	ds_read_b128 v[244:247], v133 offset:59968
	ds_read_b128 v[248:251], v133 offset:60000
	v_mfma_f32_32x32x16_bf16 v[48:63], v[212:215], v[220:223], v[48:63]
	ds_read_b128 v[212:215], v134 offset:18496
	ds_read_b128 v[220:223], v133 offset:55360
	v_mfma_f32_32x32x16_bf16 v[48:63], v[216:219], v[224:227], v[48:63]
	ds_read_b128 v[216:219], v134 offset:18528
	ds_read_b128 v[224:227], v133 offset:55392
	s_setprio 0
	v_mfma_f32_32x32x16_bf16 v[16:31], v[232:235], v[240:243], v[16:31]
	s_waitcnt lgkmcnt(13)
	v_mfma_f32_32x32x16_bf16 v[0:15], v[178:181], v[170:173], v[0:15]
	s_waitcnt lgkmcnt(7)
	v_mfma_f32_32x32x16_bf16 v[0:15], v[182:185], v[174:177], v[0:15]
	s_waitcnt vmcnt(15)
	ds_write_b128 v132, v[64:67]
	global_load_dwordx4 v[64:67], v[156:157], off offset:1792
	s_waitcnt lgkmcnt(3)
	v_mfma_f32_32x32x16_bf16 v[0:15], v[228:231], v[220:223], v[0:15]
	s_waitcnt lgkmcnt(1)
	v_mfma_f32_32x32x16_bf16 v[0:15], v[236:239], v[224:227], v[0:15]
	s_waitcnt vmcnt(15)
	ds_write_b128 v132, v[68:71] offset:4608
	global_load_dwordx4 v[68:71], v[158:159], off offset:1792
	v_mfma_f32_32x32x16_bf16 v[48:63], v[128:131], v[170:173], v[48:63]
	v_mfma_f32_32x32x16_bf16 v[32:47], v[128:131], v[186:189], v[32:47]
	s_waitcnt vmcnt(15)
	ds_write_b128 v132, v[72:75] offset:9216
	global_load_dwordx4 v[72:75], v[154:155], off offset:1792
	v_mfma_f32_32x32x16_bf16 v[16:31], v[178:181], v[186:189], v[16:31]
	v_mfma_f32_32x32x16_bf16 v[48:63], v[166:169], v[174:177], v[48:63]
	s_waitcnt vmcnt(15)
	ds_write_b128 v132, v[76:79] offset:13824
	global_load_dwordx4 v[76:79], v[152:153], off offset:1792
	v_mfma_f32_32x32x16_bf16 v[32:47], v[166:169], v[208:211], v[32:47]
	v_mfma_f32_32x32x16_bf16 v[16:31], v[182:185], v[208:211], v[16:31]
	s_waitcnt vmcnt(15)
	ds_write_b128 v132, v[80:83] offset:36864
	global_load_dwordx4 v[80:83], v[138:139], off offset:1792
	v_mfma_f32_32x32x16_bf16 v[48:63], v[212:215], v[220:223], v[48:63]
	v_mfma_f32_32x32x16_bf16 v[32:47], v[212:215], v[244:247], v[32:47]
	s_waitcnt vmcnt(15)
	ds_write_b128 v132, v[84:87] offset:41472
	global_load_dwordx4 v[84:87], v[142:143], off offset:1792
	v_mfma_f32_32x32x16_bf16 v[16:31], v[228:231], v[244:247], v[16:31]
	v_mfma_f32_32x32x16_bf16 v[48:63], v[216:219], v[224:227], v[48:63]
	s_waitcnt vmcnt(15)
	ds_write_b128 v132, v[88:91] offset:46080
	global_load_dwordx4 v[88:91], v[150:151], off offset:1792
	v_mfma_f32_32x32x16_bf16 v[32:47], v[216:219], v[248:251], v[32:47]
	s_waitcnt vmcnt(15)
	ds_write_b128 v132, v[120:123] offset:50688
	global_load_dwordx4 v[120:123], v[140:141], off offset:1792
	s_waitcnt lgkmcnt(0)
	s_barrier
	s_setprio 2
	v_mfma_f32_32x32x16_bf16 v[16:31], v[236:239], v[248:251], v[16:31]
	ds_read_b128 v[128:131], v134
	ds_read_b128 v[166:169], v134 offset:32
	ds_read_b128 v[170:173], v133 offset:36864
	ds_read_b128 v[174:177], v133 offset:36896
	ds_read_b128 v[178:181], v134 offset:4608
	ds_read_b128 v[182:185], v134 offset:4640
	ds_read_b128 v[186:189], v133 offset:41472
	ds_read_b128 v[208:211], v133 offset:41504
	ds_read_b128 v[212:215], v134 offset:64
	ds_read_b128 v[216:219], v134 offset:96
	ds_read_b128 v[220:223], v133 offset:36928
	ds_read_b128 v[224:227], v133 offset:36960
	ds_read_b128 v[228:231], v134 offset:4672
	ds_read_b128 v[232:235], v134 offset:4704
	ds_read_b128 v[236:239], v133 offset:41536
	ds_read_b128 v[240:243], v133 offset:41568
	s_setprio 0
	s_waitcnt lgkmcnt(11)
	v_mfma_f32_32x32x16_bf16 v[0:15], v[178:181], v[170:173], v[0:15]
	s_waitcnt lgkmcnt(10)
	v_mfma_f32_32x32x16_bf16 v[0:15], v[182:185], v[174:177], v[0:15]
	s_waitcnt vmcnt(15)
	ds_write_b128 v132, v[92:95] offset:18432
	global_load_dwordx4 v[92:95], v[156:157], off offset:1920
	s_waitcnt lgkmcnt(4)
	v_mfma_f32_32x32x16_bf16 v[0:15], v[228:231], v[220:223], v[0:15]
	s_waitcnt lgkmcnt(3)
	v_mfma_f32_32x32x16_bf16 v[0:15], v[232:235], v[224:227], v[0:15]
	s_waitcnt vmcnt(15)
	ds_write_b128 v132, v[96:99] offset:23040
	global_load_dwordx4 v[96:99], v[158:159], off offset:1920
	v_mfma_f32_32x32x16_bf16 v[32:47], v[128:131], v[186:189], v[32:47]
	v_mfma_f32_32x32x16_bf16 v[16:31], v[178:181], v[186:189], v[16:31]
	s_waitcnt vmcnt(15)
	ds_write_b128 v132, v[100:103] offset:27648
	global_load_dwordx4 v[100:103], v[154:155], off offset:1920
	v_mfma_f32_32x32x16_bf16 v[32:47], v[166:169], v[208:211], v[32:47]
	v_mfma_f32_32x32x16_bf16 v[16:31], v[182:185], v[208:211], v[16:31]
	s_waitcnt vmcnt(15)
	ds_write_b128 v132, v[104:107] offset:32256
	global_load_dwordx4 v[104:107], v[152:153], off offset:1920
	s_waitcnt lgkmcnt(5)
	v_mfma_f32_32x32x16_bf16 v[32:47], v[212:215], v[236:239], v[32:47]
	v_mfma_f32_32x32x16_bf16 v[16:31], v[228:231], v[236:239], v[16:31]
	s_waitcnt vmcnt(15)
	ds_write_b128 v132, v[108:111] offset:55296
	global_load_dwordx4 v[108:111], v[138:139], off offset:1920
	s_waitcnt vmcnt(15)
	ds_write_b128 v132, v[112:115] offset:59904
	global_load_dwordx4 v[112:115], v[142:143], off offset:1920
	s_waitcnt vmcnt(15)
	ds_write_b128 v132, v[116:119] offset:64512
	global_load_dwordx4 v[116:119], v[150:151], off offset:1920
	s_waitcnt vmcnt(15)
	ds_write_b128 v135, v[124:127] offset:13824
	global_load_dwordx4 v[124:127], v[140:141], off offset:1920
	s_waitcnt lgkmcnt(0)
	s_barrier
	s_setprio 2
	v_mfma_f32_32x32x16_bf16 v[32:47], v[216:219], v[240:243], v[32:47]
	v_mfma_f32_32x32x16_bf16 v[48:63], v[128:131], v[170:173], v[48:63]
	ds_read_b128 v[128:131], v134 offset:18432
	ds_read_b128 v[138:141], v134 offset:18464
	ds_read_b128 v[150:153], v133 offset:55296
	ds_read_b128 v[154:157], v133 offset:55328
	ds_read_b128 v[170:173], v134 offset:23072
	ds_read_b128 v[178:181], v133 offset:59936
	ds_read_b128 v[182:185], v134 offset:18496
	v_mfma_f32_32x32x16_bf16 v[48:63], v[166:169], v[174:177], v[48:63]
	ds_read_b128 v[166:169], v134 offset:23040
	ds_read_b128 v[174:177], v133 offset:59904
	ds_read_b128 v[186:189], v134 offset:18528
	ds_read_b128 v[208:211], v133 offset:55360
	ds_read_b128 v[228:231], v133 offset:60000
	v_mfma_f32_32x32x16_bf16 v[48:63], v[212:215], v[220:223], v[48:63]
	ds_read_b128 v[212:215], v133 offset:55392
	ds_read_b128 v[220:223], v134 offset:23136
	v_mfma_f32_32x32x16_bf16 v[48:63], v[216:219], v[224:227], v[48:63]
	ds_read_b128 v[216:219], v134 offset:23104
	ds_read_b128 v[224:227], v133 offset:59968
	s_setprio 0
	v_mfma_f32_32x32x16_bf16 v[16:31], v[232:235], v[240:243], v[16:31]
	s_waitcnt lgkmcnt(8)
	v_mfma_f32_32x32x16_bf16 v[0:15], v[166:169], v[150:153], v[0:15]
	v_mfma_f32_32x32x16_bf16 v[0:15], v[170:173], v[154:157], v[0:15]
	s_waitcnt vmcnt(15)
	ds_write_b128 v132, v[64:67]
	s_waitcnt lgkmcnt(2)
	v_mfma_f32_32x32x16_bf16 v[0:15], v[216:219], v[208:211], v[0:15]
	v_mfma_f32_32x32x16_bf16 v[0:15], v[220:223], v[212:215], v[0:15]
	s_waitcnt vmcnt(14)
	ds_write_b128 v132, v[68:71] offset:4608
	v_mfma_f32_32x32x16_bf16 v[48:63], v[128:131], v[150:153], v[48:63]
	v_mfma_f32_32x32x16_bf16 v[32:47], v[128:131], v[174:177], v[32:47]
	s_waitcnt vmcnt(13)
	ds_write_b128 v132, v[72:75] offset:9216
	v_mfma_f32_32x32x16_bf16 v[16:31], v[166:169], v[174:177], v[16:31]
	v_mfma_f32_32x32x16_bf16 v[48:63], v[138:141], v[154:157], v[48:63]
	s_waitcnt vmcnt(12)
	ds_write_b128 v132, v[76:79] offset:13824
	v_mfma_f32_32x32x16_bf16 v[32:47], v[138:141], v[178:181], v[32:47]
	v_mfma_f32_32x32x16_bf16 v[16:31], v[170:173], v[178:181], v[16:31]
	s_waitcnt vmcnt(11)
	ds_write_b128 v132, v[80:83] offset:36864
	v_mfma_f32_32x32x16_bf16 v[48:63], v[182:185], v[208:211], v[48:63]
	s_waitcnt lgkmcnt(5)
	v_mfma_f32_32x32x16_bf16 v[32:47], v[182:185], v[224:227], v[32:47]
	s_waitcnt vmcnt(10)
	ds_write_b128 v132, v[84:87] offset:41472
	v_mfma_f32_32x32x16_bf16 v[16:31], v[216:219], v[224:227], v[16:31]
	v_mfma_f32_32x32x16_bf16 v[48:63], v[186:189], v[212:215], v[48:63]
	s_waitcnt vmcnt(9)
	ds_write_b128 v132, v[88:91] offset:46080
	v_mfma_f32_32x32x16_bf16 v[32:47], v[186:189], v[228:231], v[32:47]
	s_waitcnt vmcnt(8)
	ds_write_b128 v132, v[120:123] offset:50688
	s_waitcnt lgkmcnt(0)
	s_barrier
	s_setprio 2
	v_mfma_f32_32x32x16_bf16 v[16:31], v[220:223], v[228:231], v[16:31]
	ds_read_b128 v[64:67], v134
	ds_read_b128 v[68:71], v134 offset:32
	ds_read_b128 v[72:75], v133 offset:36864
	ds_read_b128 v[76:79], v133 offset:36896
	ds_read_b128 v[80:83], v134 offset:4608
	ds_read_b128 v[84:87], v134 offset:4640
	ds_read_b128 v[88:91], v133 offset:41472
	ds_read_b128 v[120:123], v133 offset:41504
	ds_read_b128 v[128:131], v134 offset:64
	ds_read_b128 v[138:141], v134 offset:96
	ds_read_b128 v[150:153], v133 offset:36928
	ds_read_b128 v[154:157], v133 offset:36960
	ds_read_b128 v[166:169], v134 offset:4672
	ds_read_b128 v[170:173], v134 offset:4704
	ds_read_b128 v[174:177], v133 offset:41536
	ds_read_b128 v[178:181], v133 offset:41568
	s_setprio 0
	s_waitcnt lgkmcnt(11)
	v_mfma_f32_32x32x16_bf16 v[0:15], v[80:83], v[72:75], v[0:15]
	s_waitcnt lgkmcnt(10)
	v_mfma_f32_32x32x16_bf16 v[0:15], v[84:87], v[76:79], v[0:15]
	s_waitcnt vmcnt(7)
	ds_write_b128 v132, v[92:95] offset:18432
	s_waitcnt lgkmcnt(4)
	v_mfma_f32_32x32x16_bf16 v[0:15], v[166:169], v[150:153], v[0:15]
	s_waitcnt lgkmcnt(3)
	v_mfma_f32_32x32x16_bf16 v[0:15], v[170:173], v[154:157], v[0:15]
	s_waitcnt vmcnt(6)
	ds_write_b128 v132, v[96:99] offset:23040
	v_mfma_f32_32x32x16_bf16 v[32:47], v[64:67], v[88:91], v[32:47]
	v_mfma_f32_32x32x16_bf16 v[16:31], v[80:83], v[88:91], v[16:31]
	s_waitcnt vmcnt(5)
	ds_write_b128 v132, v[100:103] offset:27648
	v_mfma_f32_32x32x16_bf16 v[32:47], v[68:71], v[120:123], v[32:47]
	v_mfma_f32_32x32x16_bf16 v[16:31], v[84:87], v[120:123], v[16:31]
	s_waitcnt vmcnt(4)
	ds_write_b128 v132, v[104:107] offset:32256
	s_waitcnt lgkmcnt(5)
	v_mfma_f32_32x32x16_bf16 v[32:47], v[128:131], v[174:177], v[32:47]
	v_mfma_f32_32x32x16_bf16 v[16:31], v[166:169], v[174:177], v[16:31]
	s_waitcnt vmcnt(3)
	ds_write_b128 v132, v[108:111] offset:55296
	s_waitcnt vmcnt(2)
	ds_write_b128 v132, v[112:115] offset:59904
	s_waitcnt vmcnt(1)
	ds_write_b128 v132, v[116:119] offset:64512
	s_waitcnt vmcnt(0)
	ds_write_b128 v135, v[124:127] offset:13824
	s_waitcnt lgkmcnt(0)
	s_barrier
	s_setprio 2
	v_mfma_f32_32x32x16_bf16 v[32:47], v[138:141], v[178:181], v[32:47]
	v_mfma_f32_32x32x16_bf16 v[48:63], v[64:67], v[72:75], v[48:63]
	ds_read_b128 v[64:67], v134 offset:18432
	ds_read_b128 v[72:75], v133 offset:55296
	ds_read_b128 v[80:83], v134 offset:23040
	ds_read_b128 v[84:87], v134 offset:23072
	ds_read_b128 v[88:91], v133 offset:59904
	ds_read_b128 v[92:95], v133 offset:59936
	ds_read_b128 v[96:99], v134 offset:18496
	v_mfma_f32_32x32x16_bf16 v[48:63], v[68:71], v[76:79], v[48:63]
	ds_read_b128 v[68:71], v134 offset:18464
	ds_read_b128 v[76:79], v133 offset:55328
	ds_read_b128 v[100:103], v134 offset:18528
	ds_read_b128 v[104:107], v133 offset:55360
	ds_read_b128 v[108:111], v133 offset:55392
	ds_read_b128 v[112:115], v134 offset:23104
	ds_read_b128 v[116:119], v134 offset:23136
	v_mfma_f32_32x32x16_bf16 v[48:63], v[128:131], v[150:153], v[48:63]
	ds_read_b128 v[120:123], v133 offset:59968
	ds_read_b128 v[124:127], v133 offset:60000
	s_setprio 0
	v_mfma_f32_32x32x16_bf16 v[48:63], v[138:141], v[154:157], v[48:63]
	v_mfma_f32_32x32x16_bf16 v[16:31], v[170:173], v[178:181], v[16:31]
	s_waitcnt lgkmcnt(13)
	v_mfma_f32_32x32x16_bf16 v[0:15], v[80:83], v[72:75], v[0:15]
	s_waitcnt lgkmcnt(0)
	s_barrier
	v_mfma_f32_32x32x16_bf16 v[0:15], v[84:87], v[76:79], v[0:15]
	v_mfma_f32_32x32x16_bf16 v[0:15], v[112:115], v[104:107], v[0:15]
	v_mfma_f32_32x32x16_bf16 v[0:15], v[116:119], v[108:111], v[0:15]
	v_mfma_f32_32x32x16_bf16 v[48:63], v[64:67], v[72:75], v[48:63]
	v_mfma_f32_32x32x16_bf16 v[32:47], v[64:67], v[88:91], v[32:47]
	v_mfma_f32_32x32x16_bf16 v[16:31], v[80:83], v[88:91], v[16:31]
	v_mfma_f32_32x32x16_bf16 v[48:63], v[68:71], v[76:79], v[48:63]
	v_mfma_f32_32x32x16_bf16 v[32:47], v[68:71], v[92:95], v[32:47]
	v_mfma_f32_32x32x16_bf16 v[16:31], v[84:87], v[92:95], v[16:31]
	v_mfma_f32_32x32x16_bf16 v[48:63], v[96:99], v[104:107], v[48:63]
	v_mfma_f32_32x32x16_bf16 v[32:47], v[96:99], v[120:123], v[32:47]
	v_mfma_f32_32x32x16_bf16 v[16:31], v[112:115], v[120:123], v[16:31]
	v_mfma_f32_32x32x16_bf16 v[48:63], v[100:103], v[108:111], v[48:63]
	v_mfma_f32_32x32x16_bf16 v[32:47], v[100:103], v[124:127], v[32:47]
	v_mfma_f32_32x32x16_bf16 v[16:31], v[116:119], v[124:127], v[16:31]
	s_nop 10
	ds_write2_b32 v162, v48, v32 offset1:32
	v_add_u32_e32 v32, 0x4000, v163
	ds_write2_b32 v32, v0, v16 offset0:128 offset1:160
	v_add_u32_e32 v0, 0x4400, v163
	ds_write2_b32 v162, v49, v33 offset0:132 offset1:164
	ds_write2_b32 v0, v1, v17 offset0:4 offset1:36
	v_add_u32_e32 v1, 0x400, v162
	ds_write2_b32 v1, v50, v34 offset0:8 offset1:40
	ds_write2_b32 v0, v2, v18 offset0:136 offset1:168
	v_add_u32_e32 v0, 0x4800, v163
	s_cmpk_lt_i32 s10, 0x2000
	ds_write2_b32 v1, v51, v35 offset0:140 offset1:172
	ds_write2_b32 v0, v3, v19 offset0:12 offset1:44
	v_add_u32_e32 v0, 0x1000, v162
	v_add_u32_e32 v1, 0x5000, v163
	s_cselect_b64 s[20:21], -1, 0
	s_addk_i32 s1, 0xe000
	ds_write2_b32 v0, v52, v36 offset0:32 offset1:64
	ds_write2_b32 v1, v4, v20 offset0:160 offset1:192
	ds_write2_b32 v0, v53, v37 offset0:164 offset1:196
	v_add_u32_e32 v0, 0x5400, v163
	v_add_u32_e32 v1, 0x1400, v162
	s_ashr_i32 s1, s1, 12
	ds_write2_b32 v0, v5, v21 offset0:36 offset1:68
	ds_write2_b32 v1, v54, v38 offset0:40 offset1:72
	ds_write2_b32 v0, v6, v22 offset0:168 offset1:200
	v_add_u32_e32 v0, 0x5800, v163
	s_add_i32 s1, s1, 1
	ds_write2_b32 v1, v55, v39 offset0:172 offset1:204
	ds_write2_b32 v0, v7, v23 offset0:44 offset1:76
	v_add_u32_e32 v0, 0x2000, v162
	v_add_u32_e32 v1, 0x6000, v163
	s_and_b64 s[20:21], s[20:21], exec
	ds_write2_b32 v0, v56, v40 offset0:64 offset1:96
	ds_write2_b32 v1, v8, v24 offset0:192 offset1:224
	ds_write2_b32 v0, v57, v41 offset0:196 offset1:228
	v_add_u32_e32 v0, 0x6400, v163
	v_add_u32_e32 v1, 0x2400, v162
	s_cselect_b32 s12, 0, s1
	s_cselect_b32 s1, s36, s24
	s_cselect_b32 s16, s37, s86
	s_and_b64 s[20:21], s[28:29], exec
	ds_write2_b32 v0, v9, v25 offset0:68 offset1:100
	ds_write2_b32 v1, v58, v42 offset0:72 offset1:104
	ds_write2_b32 v0, v10, v26 offset0:200 offset1:232
	v_add_u32_e32 v0, 0x6800, v163
	s_cselect_b32 s16, s16, s93
	s_cselect_b32 s22, s1, s92
	s_ashr_i32 s1, s0, 31
	ds_write2_b32 v1, v59, v43 offset0:204 offset1:236
	ds_write2_b32 v0, v11, v27 offset0:76 offset1:108
	v_add_u32_e32 v0, 0x3000, v162
	v_add_u32_e32 v64, s10, v149
	s_lshl_b64 s[20:21], s[0:1], 2
	ds_write2_b32 v0, v60, v44 offset0:96 offset1:128
	v_add_u32_e32 v0, 0x7200, v163
	s_add_u32 s20, s22, s20
	v_add_u32_e32 v66, 16, v64
	ds_write2_b32 v0, v12, v28 offset0:96 offset1:128
	v_add_u32_e32 v0, 0x3200, v162
	s_addc_u32 s21, s16, s21
	v_lshlrev_b32_e32 v144, 2, v136
	v_ashrrev_i32_e32 v67, 31, v66
	ds_write2_b32 v0, v61, v45 offset0:100 offset1:132
	v_add_u32_e32 v0, 0x7400, v163
	v_lshl_add_u64 v[76:77], s[20:21], 0, v[144:145]
	v_lshlrev_b64 v[66:67], 12, v[66:67]
	ds_write2_b32 v0, v13, v29 offset0:100 offset1:132
	v_add_u32_e32 v0, 0x3400, v162
	v_lshl_add_u64 v[80:81], v[76:77], 0, v[66:67]
	v_add_u32_e32 v66, 32, v64
	ds_write2_b32 v0, v62, v46 offset0:104 offset1:136
	v_add_u32_e32 v0, 0x7600, v163
	v_ashrrev_i32_e32 v67, 31, v66
	ds_write2_b32 v0, v14, v30 offset0:104 offset1:136
	v_add_u32_e32 v0, 0x3600, v162
	v_lshlrev_b64 v[74:75], 12, v[66:67]
	v_add_u32_e32 v66, 48, v64
	ds_write2_b32 v0, v63, v47 offset0:108 offset1:140
	v_add_u32_e32 v0, 0x7800, v163
	v_ashrrev_i32_e32 v67, 31, v66
	ds_write2_b32 v0, v15, v31 offset0:108 offset1:140
	v_or_b32_e32 v0, s0, v136
	s_add_i32 s0, s12, s38
	v_lshlrev_b64 v[72:73], 12, v[66:67]
	v_add_u32_e32 v66, 64, v64
	s_mulk_i32 s0, 0xc00
	v_ashrrev_i32_e32 v67, 31, v66
	s_ashr_i32 s1, s0, 31
	v_lshlrev_b64 v[70:71], 12, v[66:67]
	v_add_u32_e32 v66, 0x50, v64
	s_lshl_b64 s[0:1], s[0:1], 2
	v_ashrrev_i32_e32 v65, 31, v64
	v_ashrrev_i32_e32 v67, 31, v66
	s_add_u32 s0, s94, s0
	v_ashrrev_i32_e32 v1, 31, v0
	v_lshlrev_b64 v[96:97], 12, v[64:65]
	v_lshlrev_b64 v[68:69], 12, v[66:67]
	v_add_u32_e32 v66, 0x60, v64
	v_add_u32_e32 v64, 0x70, v64
	s_addc_u32 s1, s95, s1
	v_lshlrev_b64 v[16:17], 2, v[0:1]
	v_ashrrev_i32_e32 v67, 31, v66
	v_ashrrev_i32_e32 v65, 31, v64
	v_lshl_add_u64 v[62:63], s[0:1], 0, v[16:17]
	s_mov_b32 s0, 0x902000
	v_lshlrev_b64 v[66:67], 12, v[66:67]
	v_lshlrev_b64 v[64:65], 12, v[64:65]
	v_add_co_u32_e32 v98, vcc, s0, v62
	s_mov_b64 s[0:1], 0x902000
	v_lshl_add_u64 v[78:79], v[76:77], 0, v[96:97]
	v_lshl_add_u64 v[82:83], v[76:77], 0, v[74:75]
	v_lshl_add_u64 v[84:85], v[76:77], 0, v[72:73]
	v_lshl_add_u64 v[86:87], v[76:77], 0, v[70:71]
	v_lshl_add_u64 v[88:89], v[76:77], 0, v[68:69]
	v_lshl_add_u64 v[90:91], v[76:77], 0, v[66:67]
	v_lshl_add_u64 v[76:77], v[76:77], 0, v[64:65]
	v_addc_co_u32_e32 v99, vcc, 0, v63, vcc
	v_lshl_add_u64 v[62:63], v[62:63], 0, s[0:1]
	global_load_dwordx4 v[0:3], v[76:77], off offset:16
	global_load_dwordx4 v[4:7], v[76:77], off
	global_load_dwordx4 v[8:11], v[90:91], off offset:16
	global_load_dwordx4 v[12:15], v[90:91], off
	global_load_dwordx4 v[18:21], v[88:89], off offset:16
	global_load_dwordx4 v[22:25], v[88:89], off
	global_load_dwordx4 v[26:29], v[86:87], off offset:16
	global_load_dwordx4 v[30:33], v[86:87], off
	global_load_dwordx4 v[34:37], v[84:85], off offset:16
	global_load_dwordx4 v[38:41], v[84:85], off
	global_load_dwordx4 v[42:45], v[82:83], off offset:16
	global_load_dwordx4 v[46:49], v[82:83], off
	global_load_dwordx4 v[50:53], v[80:81], off offset:16
	global_load_dwordx4 v[54:57], v[80:81], off
	global_load_dwordx4 v[58:61], v[78:79], off offset:16
	v_add_u32_e32 v92, v160, v161
	global_load_dwordx4 v[76:79], v[78:79], off
	s_waitcnt lgkmcnt(0)
	s_barrier
	s_setprio 2
	global_load_dwordx4 v[80:83], v[98:99], off
	global_load_dwordx4 v[84:87], v[62:63], off offset:16
	ds_read_b128 v[88:91], v92
	ds_read_b128 v[92:95], v92 offset:16
	v_lshl_add_u64 v[96:97], s[92:93], 0, v[96:97]
	v_lshl_add_u64 v[96:97], v[96:97], 0, v[16:17]
	v_lshl_add_u64 v[74:75], s[92:93], 0, v[74:75]
	v_lshl_add_u64 v[74:75], v[74:75], 0, v[16:17]
	s_add_i32 s9, s9, s5
	s_add_i32 s8, s8, s11
	s_add_i32 s6, s6, s87
	s_cmpk_lt_i32 s6, 0x600
	s_waitcnt vmcnt(1) lgkmcnt(1)
	v_pk_fma_f32 v[76:77], v[88:89], v[80:81], v[76:77]
	v_pk_fma_f32 v[78:79], v[90:91], v[82:83], v[78:79]
	s_waitcnt vmcnt(0) lgkmcnt(0)
	v_pk_fma_f32 v[58:59], v[92:93], v[84:85], v[58:59]
	v_pk_fma_f32 v[60:61], v[94:95], v[86:87], v[60:61]
	global_store_dwordx4 v[96:97], v[76:79], off
	global_store_dwordx4 v[96:97], v[58:61], off offset:16
	global_load_dwordx4 v[58:61], v[98:99], off
	v_add_u32_e32 v84, s10, v164
	global_load_dwordx4 v[76:79], v[62:63], off offset:16
	v_ashrrev_i32_e32 v85, 31, v84
	ds_read_b128 v[80:83], v165
	v_lshlrev_b64 v[88:89], 12, v[84:85]
	ds_read_b128 v[84:87], v165 offset:16
	v_lshl_add_u64 v[88:89], s[92:93], 0, v[88:89]
	v_lshl_add_u64 v[88:89], v[88:89], 0, v[16:17]
	s_waitcnt vmcnt(1) lgkmcnt(1)
	v_pk_fma_f32 v[54:55], v[80:81], v[58:59], v[54:55]
	v_pk_fma_f32 v[56:57], v[82:83], v[60:61], v[56:57]
	s_waitcnt vmcnt(0) lgkmcnt(0)
	v_pk_fma_f32 v[50:51], v[84:85], v[76:77], v[50:51]
	v_pk_fma_f32 v[52:53], v[86:87], v[78:79], v[52:53]
	global_store_dwordx4 v[88:89], v[54:57], off
	global_store_dwordx4 v[88:89], v[50:53], off offset:16
	global_load_dwordx4 v[50:53], v[98:99], off
	ds_read_b128 v[58:61], v165 offset:8448
	global_load_dwordx4 v[54:57], v[62:63], off offset:16
	ds_read_b128 v[76:79], v165 offset:8464
	s_waitcnt vmcnt(1) lgkmcnt(1)
	v_pk_fma_f32 v[46:47], v[58:59], v[50:51], v[46:47]
	v_pk_fma_f32 v[48:49], v[60:61], v[52:53], v[48:49]
	s_waitcnt vmcnt(0) lgkmcnt(0)
	v_pk_fma_f32 v[42:43], v[76:77], v[54:55], v[42:43]
	v_pk_fma_f32 v[44:45], v[78:79], v[56:57], v[44:45]
	global_store_dwordx4 v[74:75], v[46:49], off
	global_store_dwordx4 v[74:75], v[42:45], off offset:16
	global_load_dwordx4 v[42:45], v[98:99], off
	ds_read_b128 v[50:53], v165 offset:16896
	global_load_dwordx4 v[46:49], v[62:63], off offset:16
	ds_read_b128 v[54:57], v165 offset:16912
	v_lshl_add_u64 v[58:59], s[92:93], 0, v[72:73]
	v_lshl_add_u64 v[58:59], v[58:59], 0, v[16:17]
	s_waitcnt vmcnt(1) lgkmcnt(1)
	v_pk_fma_f32 v[38:39], v[50:51], v[42:43], v[38:39]
	v_pk_fma_f32 v[40:41], v[52:53], v[44:45], v[40:41]
	s_waitcnt vmcnt(0) lgkmcnt(0)
	v_pk_fma_f32 v[34:35], v[54:55], v[46:47], v[34:35]
	v_pk_fma_f32 v[36:37], v[56:57], v[48:49], v[36:37]
	global_store_dwordx4 v[58:59], v[38:41], off
	global_store_dwordx4 v[58:59], v[34:37], off offset:16
	global_load_dwordx4 v[34:37], v[98:99], off
	ds_read_b128 v[42:45], v165 offset:25344
	global_load_dwordx4 v[38:41], v[62:63], off offset:16
	ds_read_b128 v[46:49], v165 offset:25360
	v_lshl_add_u64 v[50:51], s[92:93], 0, v[70:71]
	v_lshl_add_u64 v[50:51], v[50:51], 0, v[16:17]
	s_waitcnt vmcnt(1) lgkmcnt(1)
	v_pk_fma_f32 v[30:31], v[42:43], v[34:35], v[30:31]
	v_pk_fma_f32 v[32:33], v[44:45], v[36:37], v[32:33]
	s_waitcnt vmcnt(0) lgkmcnt(0)
	v_pk_fma_f32 v[26:27], v[46:47], v[38:39], v[26:27]
	v_pk_fma_f32 v[28:29], v[48:49], v[40:41], v[28:29]
	global_store_dwordx4 v[50:51], v[30:33], off
	global_store_dwordx4 v[50:51], v[26:29], off offset:16
	global_load_dwordx4 v[26:29], v[98:99], off
	ds_read_b128 v[34:37], v165 offset:33792
	global_load_dwordx4 v[30:33], v[62:63], off offset:16
	ds_read_b128 v[38:41], v165 offset:33808
	v_lshl_add_u64 v[42:43], s[92:93], 0, v[68:69]
	v_lshl_add_u64 v[42:43], v[42:43], 0, v[16:17]
	s_waitcnt vmcnt(1) lgkmcnt(1)
	v_pk_fma_f32 v[22:23], v[34:35], v[26:27], v[22:23]
	v_pk_fma_f32 v[24:25], v[36:37], v[28:29], v[24:25]
	s_waitcnt vmcnt(0) lgkmcnt(0)
	v_pk_fma_f32 v[18:19], v[38:39], v[30:31], v[18:19]
	v_pk_fma_f32 v[20:21], v[40:41], v[32:33], v[20:21]
	global_store_dwordx4 v[42:43], v[22:25], off
	global_store_dwordx4 v[42:43], v[18:21], off offset:16
	global_load_dwordx4 v[18:21], v[98:99], off
	ds_read_b128 v[26:29], v165 offset:42240
	global_load_dwordx4 v[22:25], v[62:63], off offset:16
	ds_read_b128 v[30:33], v165 offset:42256
	v_lshl_add_u64 v[34:35], s[92:93], 0, v[66:67]
	v_lshl_add_u64 v[34:35], v[34:35], 0, v[16:17]
	s_waitcnt vmcnt(1) lgkmcnt(1)
	v_pk_fma_f32 v[12:13], v[26:27], v[18:19], v[12:13]
	v_pk_fma_f32 v[14:15], v[28:29], v[20:21], v[14:15]
	s_waitcnt vmcnt(0) lgkmcnt(0)
	v_pk_fma_f32 v[8:9], v[30:31], v[22:23], v[8:9]
	v_pk_fma_f32 v[10:11], v[32:33], v[24:25], v[10:11]
	global_store_dwordx4 v[34:35], v[12:15], off
	global_store_dwordx4 v[34:35], v[8:11], off offset:16
	global_load_dwordx4 v[8:11], v[98:99], off
	v_lshl_add_u64 v[18:19], s[92:93], 0, v[64:65]
	global_load_dwordx4 v[12:15], v[62:63], off offset:16
	v_lshl_add_u64 v[24:25], v[18:19], 0, v[16:17]
	ds_read_b128 v[16:19], v165 offset:50688
	ds_read_b128 v[20:23], v165 offset:50704
	s_setprio 0
	s_waitcnt vmcnt(1) lgkmcnt(1)
	v_pk_fma_f32 v[4:5], v[16:17], v[8:9], v[4:5]
	v_pk_fma_f32 v[6:7], v[18:19], v[10:11], v[6:7]
	s_waitcnt vmcnt(0) lgkmcnt(0)
	v_pk_fma_f32 v[0:1], v[20:21], v[12:13], v[0:1]
	v_pk_fma_f32 v[2:3], v[22:23], v[14:15], v[2:3]
	global_store_dwordx4 v[24:25], v[4:7], off
	global_store_dwordx4 v[24:25], v[0:3], off offset:16
	s_barrier
	s_cbranch_scc1 .LBB0_802
	v_mov_b32_e32 v243, 0x13c00
